# attention loop: VALU removed from post-barrier segment heads (p0 exps and l-update moved before barrier, head p1 exps spread into later MFMA steps); gates sqrt slimmed
# speedup vs baseline: 1.0083x; 1.0025x over previous
; __device__ __forceinline__ void qkt(f32x16& p0, f32x16& p1, const char* Kn, const bf16x8* qr, int r32, int hi) {
;     const char* Kr = Kn + KR_OFF;
;     p0 = f32x16{}; p1 = f32x16{};
;     __builtin_amdgcn_s_setprio(1);
; #pragma unroll
;     for (int d0 = 0; d0 < 8; ++d0) { const int cb = (d0 * 16 + hi * 8) * 2;
;         const bf16x8 b0 = *reinterpret_cast<const bf16x8*>(Kn + KNSWZ(r32, cb));
;         const bf16x8 b1 = *reinterpret_cast<const bf16x8*>(Kn + KNSWZ(32 + r32, cb));
;         p0 = __builtin_amdgcn_mfma_f32_32x32x16_bf16(b0, qr[d0], p0, 0, 0, 0);
;         p1 = __builtin_amdgcn_mfma_f32_32x32x16_bf16(b1, qr[d0], p1, 0, 0, 0); }
; #pragma unroll
;     for (int d0 = 0; d0 < 4; ++d0) { const int cb = (d0 * 16 + hi * 8) * 2;
;         const bf16x8 b0 = *reinterpret_cast<const bf16x8*>(Kr + KRSWZ(r32, cb));
;         const bf16x8 b1 = *reinterpret_cast<const bf16x8*>(Kr + KRSWZ(32 + r32, cb));
;         p0 = __builtin_amdgcn_mfma_f32_32x32x16_bf16(b0, qr[8 + d0], p0, 0, 0, 0);
;         p1 = __builtin_amdgcn_mfma_f32_32x32x16_bf16(b1, qr[8 + d0], p1, 0, 0, 0); }
.LBB0_216:
	s_mul_i32 s0, s9, 0x6000
	s_add_i32 s14, s0, 0
	s_lshl_b32 s13, s9, 14
	s_add_i32 s16, s14, s6
	s_add_i32 s17, s7, s13
	s_add_i32 s18, s14, s8
	s_mov_b32 s13, s10
	s_mov_b32 s10, s15
	s_mul_i32 s0, s13, 0x6000
	s_add_i32 s0, s0, 0
	s_setprio 1
	v_add_u32_e32 v84, s0, v207
	ds_read_b128 v[80:83], v84
	ds_read_b128 v[84:87], v84 offset:8192
	v_add_u32_e32 v168, s0, v210
	ds_read_b128 v[196:199], v168
	ds_read_b128 v[168:171], v168 offset:8192
	v_add_u32_e32 v184, s0, v218
	s_waitcnt lgkmcnt(0)
	v_mfma_f32_32x32x16_bf16 v[96:111], v[80:83], v[156:159], 0
	v_mfma_f32_32x32x16_bf16 v[80:95], v[84:87], v[156:159], 0
	v_mfma_f32_32x32x16_bf16 v[96:111], v[196:199], v[152:155], v[96:111]
	v_mfma_f32_32x32x16_bf16 v[80:95], v[168:171], v[152:155], v[80:95]
	ds_read_b128 v[168:171], v184
	ds_read_b128 v[196:199], v184 offset:8192
	v_add_u32_e32 v184, s0, v221
	s_mov_b32 m0, s16
	s_add_u32 s100, s72, 0x26500000
	s_addc_u32 s101, s73, 0
	global_load_lds_dwordx4 v178, s[100:101]
	s_waitcnt lgkmcnt(0)
	v_mfma_f32_32x32x16_bf16 v[96:111], v[168:171], v[148:151], v[96:111]
	v_mfma_f32_32x32x16_bf16 v[80:95], v[196:199], v[148:151], v[80:95]
	ds_read_b128 v[168:171], v184
	ds_read_b128 v[196:199], v184 offset:8192
	v_add_u32_e32 v184, s0, v222
	s_waitcnt lgkmcnt(0)
	v_mfma_f32_32x32x16_bf16 v[96:111], v[168:171], v[144:147], v[96:111]
	v_mfma_f32_32x32x16_bf16 v[80:95], v[196:199], v[144:147], v[80:95]
	ds_read_b128 v[168:171], v184
	ds_read_b128 v[196:199], v184 offset:8192
	v_add_u32_e32 v184, s0, v223
	s_add_i32 m0, s16, 0x400
	s_nop 0
	global_load_lds_dwordx4 v180, s[100:101]
	s_waitcnt lgkmcnt(0)
	v_mfma_f32_32x32x16_bf16 v[96:111], v[168:171], v[140:143], v[96:111]
	v_mfma_f32_32x32x16_bf16 v[80:95], v[196:199], v[140:143], v[80:95]
	ds_read_b128 v[168:171], v184
	ds_read_b128 v[196:199], v184 offset:8192
	v_add_u32_e32 v184, s0, v224
	v_exp_f32_e32 v233, v73
	s_waitcnt lgkmcnt(0)
	v_mfma_f32_32x32x16_bf16 v[96:111], v[168:171], v[136:139], v[96:111]
	v_mfma_f32_32x32x16_bf16 v[80:95], v[196:199], v[136:139], v[80:95]
	ds_read_b128 v[168:171], v184
	ds_read_b128 v[196:199], v184 offset:8192
	v_add_u32_e32 v184, s0, v225
	s_mov_b32 m0, s17
	s_add_u32 s100, s72, 0x26500100
	s_addc_u32 s101, s73, 0
	global_load_lds_dwordx4 v176, s[100:101]
	v_exp_f32_e32 v250, v74
	s_waitcnt lgkmcnt(0)
	v_mfma_f32_32x32x16_bf16 v[96:111], v[168:171], v[132:135], v[96:111]
	v_mfma_f32_32x32x16_bf16 v[80:95], v[196:199], v[132:135], v[80:95]
	ds_read_b128 v[168:171], v184
	ds_read_b128 v[196:199], v184 offset:8192
	v_add_u32_e32 v184, s0, v226
	v_exp_f32_e32 v200, v75
	s_waitcnt lgkmcnt(0)
	v_mfma_f32_32x32x16_bf16 v[96:111], v[168:171], v[128:131], v[96:111]
	v_mfma_f32_32x32x16_bf16 v[80:95], v[196:199], v[128:131], v[80:95]
	ds_read_b128 v[168:171], v184 offset:16384
	ds_read_b128 v[196:199], v184 offset:20480
	v_add_u32_e32 v184, s0, v227
	s_add_i32 m0, s17, 0x400
	s_add_u32 s100, s72, 0x26500180
	s_addc_u32 s101, s73, 0
	global_load_lds_dwordx4 v176, s[100:101]
	v_exp_f32_e32 v195, v76
	s_waitcnt lgkmcnt(0)
	v_mfma_f32_32x32x16_bf16 v[96:111], v[168:171], v[124:127], v[96:111]
	v_mfma_f32_32x32x16_bf16 v[80:95], v[196:199], v[124:127], v[80:95]
	ds_read_b128 v[168:171], v184 offset:16384
	ds_read_b128 v[196:199], v184 offset:20480
	v_add_u32_e32 v184, s0, v228
	v_exp_f32_e32 v172, v77
	s_waitcnt lgkmcnt(0)
	v_mfma_f32_32x32x16_bf16 v[96:111], v[168:171], v[120:123], v[96:111]
	v_mfma_f32_32x32x16_bf16 v[80:95], v[196:199], v[120:123], v[80:95]
	ds_read_b128 v[168:171], v184 offset:16384
	ds_read_b128 v[196:199], v184 offset:20480
	v_add_u32_e32 v184, s0, v229
	s_add_i32 m0, s18, 0x4000
	s_add_u32 s100, s72, 0x21204000
	s_addc_u32 s101, s73, 0
	global_load_lds_dwordx4 v174, s[100:101]
	v_exp_f32_e32 v173, v78
	s_waitcnt lgkmcnt(0)
	v_mfma_f32_32x32x16_bf16 v[96:111], v[168:171], v[116:119], v[96:111]
	v_mfma_f32_32x32x16_bf16 v[80:95], v[196:199], v[116:119], v[80:95]
	ds_read_b128 v[168:171], v184 offset:16384
	ds_read_b128 v[196:199], v184 offset:20480
	v_exp_f32_e32 v184, v68
	v_exp_f32_e32 v79, v79
	s_waitcnt lgkmcnt(0)
; #define SBAR() __builtin_amdgcn_sched_barrier(0)
; __device__ __forceinline__ void finishSM(f32x16& p0, f32x16& p1, float alpha, float& l_reg, bf16x8& pa0, bf16x8& pa1, bf16x8& pa2, bf16x8& pa3) {
; #pragma unroll
;     for (int r = 0; r < 16; ++r) p1[r] = __builtin_amdgcn_exp2f(p1[r]);
;     float ps = 0;
; #pragma unroll
;     for (int r = 0; r < 16; ++r) ps += p0[r];
; #pragma unroll
;     for (int r = 0; r < 16; ++r) ps += p1[r];
;     { auto rr = __builtin_amdgcn_permlane32_swap(__float_as_uint(ps), __float_as_uint(ps), false, false);
;       ps = __uint_as_float(rr[0]) + __uint_as_float(rr[1]); }
;     l_reg = l_reg * alpha + ps;
;     ...
;     PK4(p0, 0, pa0); PK4(p0, 8, pa1); PK4(p1, 0, pa2); PK4(p1, 8, pa3);
; template <int D0> __device__ __forceinline__ void pv_one(f32x16& od, int vb, bf16x8 pa0, bf16x8 pa1, bf16x8 pa2, bf16x8 pa3) {
;     const s16x4 l0 = tr_read<v_rd_off(D0, 0, 0)>(vb), h0 = tr_read<v_rd_off(D0, 0, 1)>(vb), l1 = tr_read<v_rd_off(D0, 1, 0)>(vb), h1 = tr_read<v_rd_off(D0, 1, 1)>(vb);
;     const s16x4 l2 = tr_read<v_rd_off(D0, 2, 0)>(vb), h2 = tr_read<v_rd_off(D0, 2, 1)>(vb), l3 = tr_read<v_rd_off(D0, 3, 0)>(vb), h3 = tr_read<v_rd_off(D0, 3, 1)>(vb);
;     asm volatile("s_waitcnt lgkmcnt(0)" ::: "memory"); SBAR();
;     ...
;     od = __builtin_amdgcn_mfma_f32_32x32x16_bf16(pa0, PK(l0, h0), od, 0, 0, 0);
;     od = __builtin_amdgcn_mfma_f32_32x32x16_bf16(pa1, PK(l1, h1), od, 0, 0, 0);
;     od = __builtin_amdgcn_mfma_f32_32x32x16_bf16(pa2, PK(l2, h2), od, 0, 0, 0);
;     od = __builtin_amdgcn_mfma_f32_32x32x16_bf16(pa3, PK(l3, h3), od, 0, 0, 0);
;     ...
; }
; __device__ __forceinline__ void pv_d0(f32x16* o, int vb, bf16x8 pa0, bf16x8 pa1, bf16x8 pa2, bf16x8 pa3) {
;     pv_one<0>(o[0], vb, pa0, pa1, pa2, pa3); pv_one<1>(o[1], vb, pa0, pa1, pa2, pa3); pv_one<2>(o[2], vb, pa0, pa1, pa2, pa3); pv_one<3>(o[3], vb, pa0, pa1, pa2, pa3);
	v_mfma_f32_32x32x16_bf16 v[96:111], v[168:171], v[112:115], v[96:111]
	v_exp_f32_e32 v168, v64
	v_add_f32_e32 v64, 0, v247
	v_add_f32_e32 v64, v249, v64
	v_add_f32_e32 v64, v245, v64
	v_add_f32_e32 v64, v248, v64
	v_add_f32_e32 v64, v244, v64
	v_add_f32_e32 v64, v246, v64
	v_add_f32_e32 v64, v242, v64
	v_add_f32_e32 v64, v243, v64
	v_add_f32_e32 v64, v239, v64
	v_add_f32_e32 v64, v241, v64
	v_add_f32_e32 v64, v238, v64
	v_add_f32_e32 v64, v240, v64
	v_add_f32_e32 v64, v235, v64
	v_exp_f32_e32 v169, v65
	v_add_f32_e32 v64, v237, v64
	v_exp_f32_e32 v170, v66
	v_add_f32_e32 v64, v234, v64
	v_exp_f32_e32 v171, v67
	v_add_f32_e32 v64, v236, v64
	v_add_f32_e32 v64, v168, v64
	v_mfma_f32_32x32x16_bf16 v[80:95], v[196:199], v[112:115], v[80:95]
	v_exp_f32_e32 v196, v69
	v_add_f32_e32 v64, v169, v64
	v_exp_f32_e32 v197, v70
	v_add_f32_e32 v64, v170, v64
	v_exp_f32_e32 v198, v71
	v_add_f32_e32 v64, v171, v64
	v_exp_f32_e32 v199, v72
	v_add_f32_e32 v64, v184, v64
	v_add_f32_e32 v64, v196, v64
	v_add_f32_e32 v64, v197, v64
	v_add_f32_e32 v64, v198, v64
	v_add_f32_e32 v64, v199, v64
	v_add_f32_e32 v64, v233, v64
	v_add_f32_e32 v64, v250, v64
	v_add_f32_e32 v64, v200, v64
	v_add_f32_e32 v64, v195, v64
	v_add_f32_e32 v64, v172, v64
	v_add_f32_e32 v64, v173, v64
	v_add_f32_e32 v231, v79, v64
	v_mov_b32_e32 v232, v231
	v_cvt_pk_bf16_f32 v64, v247, v249
	v_cvt_pk_bf16_f32 v65, v245, v248
	v_cvt_pk_bf16_f32 v66, v244, v246
	s_nop 1
	v_permlane32_swap_b32_e32 v231, v232
	v_cvt_pk_bf16_f32 v67, v242, v243
	v_permlane32_swap_b32_e32 v64, v66
	v_cvt_pk_bf16_f32 v68, v239, v241
	v_cvt_pk_bf16_f32 v69, v238, v240
	v_cvt_pk_bf16_f32 v70, v235, v237
	v_cvt_pk_bf16_f32 v71, v234, v236
	v_cvt_pk_bf16_f32 v72, v168, v169
	v_cvt_pk_bf16_f32 v73, v170, v171
	v_cvt_pk_bf16_f32 v74, v184, v196
	v_cvt_pk_bf16_f32 v75, v197, v198
	v_cvt_pk_bf16_f32 v76, v199, v233
	v_cvt_pk_bf16_f32 v77, v250, v200
	v_cvt_pk_bf16_f32 v78, v195, v172
	v_cvt_pk_bf16_f32 v79, v173, v79
	v_permlane32_swap_b32_e32 v65, v67
	v_permlane32_swap_b32_e32 v68, v70
	v_permlane32_swap_b32_e32 v69, v71
	v_permlane32_swap_b32_e32 v72, v74
	v_permlane32_swap_b32_e32 v73, v75
	v_permlane32_swap_b32_e32 v76, v78
	v_permlane32_swap_b32_e32 v77, v79
	s_setprio 0
	s_lshl_b32 s15, s15, 14
	v_add_u32_e32 v172, s15, v205
	ds_read_b64_tr_b16 v[168:169], v172 offset:0
	ds_read_b64_tr_b16 v[170:171], v172 offset:0x800
	ds_read_b64_tr_b16 v[196:197], v172 offset:0x1000
	ds_read_b64_tr_b16 v[198:199], v172 offset:0x1800
	ds_read_b64_tr_b16 v[234:235], v172 offset:0x2000
	ds_read_b64_tr_b16 v[236:237], v172 offset:0x2800
	ds_read_b64_tr_b16 v[238:239], v172 offset:0x3000
	ds_read_b64_tr_b16 v[240:241], v172 offset:0x3800
	s_waitcnt lgkmcnt(0)
	s_nop 0
	v_mfma_f32_32x32x16_bf16 v[0:15], v[64:67], v[168:171], v[0:15]
	ds_read_b64_tr_b16 v[168:169], v172 offset:0x200
	ds_read_b64_tr_b16 v[170:171], v172 offset:0xa00
	v_mfma_f32_32x32x16_bf16 v[0:15], v[68:71], v[196:199], v[0:15]
	ds_read_b64_tr_b16 v[196:197], v172 offset:0x1200
	ds_read_b64_tr_b16 v[198:199], v172 offset:0x1a00
	v_mfma_f32_32x32x16_bf16 v[0:15], v[72:75], v[234:237], v[0:15]
	ds_read_b64_tr_b16 v[234:235], v172 offset:0x2200
	ds_read_b64_tr_b16 v[236:237], v172 offset:0x2a00
	v_mfma_f32_32x32x16_bf16 v[0:15], v[76:79], v[238:241], v[0:15]
	ds_read_b64_tr_b16 v[238:239], v172 offset:0x3200
	ds_read_b64_tr_b16 v[240:241], v172 offset:0x3a00
	s_waitcnt lgkmcnt(0)
	v_mfma_f32_32x32x16_bf16 v[48:63], v[64:67], v[168:171], v[48:63]
	ds_read_b64_tr_b16 v[168:169], v172 offset:0x400
	ds_read_b64_tr_b16 v[170:171], v172 offset:0xc00
	v_mfma_f32_32x32x16_bf16 v[48:63], v[68:71], v[196:199], v[48:63]
	ds_read_b64_tr_b16 v[196:197], v172 offset:0x1400
	ds_read_b64_tr_b16 v[198:199], v172 offset:0x1c00
	v_mfma_f32_32x32x16_bf16 v[48:63], v[72:75], v[234:237], v[48:63]
	ds_read_b64_tr_b16 v[234:235], v172 offset:0x2400
	ds_read_b64_tr_b16 v[236:237], v172 offset:0x2c00
	v_mfma_f32_32x32x16_bf16 v[48:63], v[76:79], v[238:241], v[48:63]
	ds_read_b64_tr_b16 v[238:239], v172 offset:0x3400
	ds_read_b64_tr_b16 v[240:241], v172 offset:0x3c00
	s_waitcnt lgkmcnt(0)
	v_mfma_f32_32x32x16_bf16 v[32:47], v[64:67], v[168:171], v[32:47]
	ds_read_b64_tr_b16 v[168:169], v172 offset:0x600
	ds_read_b64_tr_b16 v[170:171], v172 offset:0xe00
	v_mfma_f32_32x32x16_bf16 v[32:47], v[68:71], v[196:199], v[32:47]
	ds_read_b64_tr_b16 v[196:197], v172 offset:0x1600
	ds_read_b64_tr_b16 v[198:199], v172 offset:0x1e00
	v_mfma_f32_32x32x16_bf16 v[32:47], v[72:75], v[234:237], v[32:47]
	ds_read_b64_tr_b16 v[234:235], v172 offset:0x2600
	ds_read_b64_tr_b16 v[236:237], v172 offset:0x2e00
	v_mfma_f32_32x32x16_bf16 v[32:47], v[76:79], v[238:241], v[32:47]
	ds_read_b64_tr_b16 v[238:239], v172 offset:0x3600
	ds_read_b64_tr_b16 v[240:241], v172 offset:0x3e00
	s_waitcnt lgkmcnt(0)
	v_mfma_f32_32x32x16_bf16 v[16:31], v[64:67], v[168:171], v[16:31]
	v_max_f32_e32 v64, v97, v97
	v_max_f32_e32 v65, v96, v96
	v_max_f32_e32 v64, v65, v64
	v_max3_f32 v64, v64, v98, v99
	v_max3_f32 v64, v64, v100, v101
	v_max3_f32 v64, v64, v102, v103
	v_max3_f32 v64, v64, v104, v105
	v_mfma_f32_32x32x16_bf16 v[16:31], v[68:71], v[196:199], v[16:31]
	v_max3_f32 v64, v64, v106, v107
	v_max3_f32 v64, v64, v108, v109
	v_max3_f32 v64, v64, v110, v111
	v_max3_f32 v64, v64, v80, v81
	v_max3_f32 v64, v64, v82, v83
	v_max3_f32 v64, v64, v84, v85
	v_max3_f32 v64, v64, v86, v87
	v_mfma_f32_32x32x16_bf16 v[16:31], v[72:75], v[234:237], v[16:31]
	v_max3_f32 v64, v64, v88, v89
	v_max3_f32 v64, v64, v90, v91
	v_max3_f32 v64, v64, v92, v93
	v_max3_f32 v64, v64, v94, v95
	v_mov_b32_e32 v65, v64
	s_nop 1
	v_permlane32_swap_b32_e32 v64, v65
	v_max_f32_e32 v65, v65, v65
	v_max_f32_e32 v64, v64, v64
	v_mfma_f32_32x32x16_bf16 v[16:31], v[76:79], v[238:241], v[16:31]
	v_max_f32_e32 v64, v64, v65
	v_sub_f32_e32 v65, v64, v182
	s_mov_b32 s0, 0x41300000
	v_cmp_ge_f32_e32 vcc, s0, v65
	s_cmp_eq_u64 vcc, exec
	v_max_f32_e32 v65, v182, v182
	s_cselect_b64 vcc, -1, 0
	v_max_f32_e32 v64, v65, v64
	v_cndmask_b32_e32 v184, v64, v182, vcc
	v_cmp_eq_f32_e64 s[0:1], 0, v184
	s_cmp_eq_u64 s[0:1], exec
	s_cbranch_scc0 .LBB0_228

; template <bool FIRST>
; __device__ __forceinline__ void partialSM(f32x16& p0, f32x16& p1, float& m_reg, float& mn, float& alpha) {
;     ...
;         for (int r = 0; r < 16; ++r) p0[r] = p0[r] - mn;
; #pragma unroll
;         for (int r = 0; r < 16; ++r) p1[r] = p1[r] - mn; }
; #pragma unroll
;     for (int r = 0; r < 16; ++r) p0[r] = __builtin_amdgcn_exp2f(p0[r]);
; __device__ __forceinline__ void qkt(f32x16& p0, f32x16& p1, const char* Kn, const bf16x8* qr, int r32, int hi) {
;     const char* Kr = Kn + KR_OFF;
;     p0 = f32x16{}; p1 = f32x16{};
;     __builtin_amdgcn_s_setprio(1);
; #pragma unroll
;     for (int d0 = 0; d0 < 8; ++d0) { const int cb = (d0 * 16 + hi * 8) * 2;
;         const bf16x8 b0 = *reinterpret_cast<const bf16x8*>(Kn + KNSWZ(r32, cb));
;         const bf16x8 b1 = *reinterpret_cast<const bf16x8*>(Kn + KNSWZ(32 + r32, cb));
;         p0 = __builtin_amdgcn_mfma_f32_32x32x16_bf16(b0, qr[d0], p0, 0, 0, 0);
;         p1 = __builtin_amdgcn_mfma_f32_32x32x16_bf16(b1, qr[d0], p1, 0, 0, 0); }
; #pragma unroll
;     for (int d0 = 0; d0 < 4; ++d0) { const int cb = (d0 * 16 + hi * 8) * 2;
;         const bf16x8 b0 = *reinterpret_cast<const bf16x8*>(Kr + KRSWZ(r32, cb));
;         const bf16x8 b1 = *reinterpret_cast<const bf16x8*>(Kr + KRSWZ(32 + r32, cb));
;         p0 = __builtin_amdgcn_mfma_f32_32x32x16_bf16(b0, qr[8 + d0], p0, 0, 0, 0);
;         p1 = __builtin_amdgcn_mfma_f32_32x32x16_bf16(b1, qr[8 + d0], p1, 0, 0, 0); }
.LBB0_221:
	v_exp_f32_e32 v182, v98
	v_exp_f32_e32 v172, v96
	v_exp_f32_e32 v173, v97
	v_exp_f32_e32 v195, v99
	v_exp_f32_e32 v196, v100
	v_exp_f32_e32 v197, v101
	v_exp_f32_e32 v198, v102
	v_exp_f32_e32 v199, v103
	v_exp_f32_e32 v200, v104
	v_exp_f32_e32 v234, v105
	v_exp_f32_e32 v235, v106
	v_exp_f32_e32 v236, v107
	v_exp_f32_e32 v237, v108
	v_exp_f32_e32 v238, v109
	v_exp_f32_e32 v239, v110
	v_exp_f32_e32 v240, v111
	s_mul_i32 s0, s10, 0x6000
	s_add_i32 s16, s0, 0
	s_add_i32 s17, s16, s6
	s_add_i32 s18, s16, s8
	s_waitcnt vmcnt(0) lgkmcnt(0)
	s_barrier
	s_add_i32 s15, s7, s15
	s_setprio 1
	v_add_u32_e32 v68, s14, v207
	ds_read_b128 v[64:67], v68
	ds_read_b128 v[68:71], v68 offset:8192
	v_add_u32_e32 v186, s14, v210
	ds_read_b128 v[168:171], v186
	ds_read_b128 v[186:189], v186 offset:8192
	s_waitcnt lgkmcnt(0)
	v_mfma_f32_32x32x16_bf16 v[96:111], v[64:67], v[156:159], 0
	v_mfma_f32_32x32x16_bf16 v[64:79], v[68:71], v[156:159], 0
	v_mfma_f32_32x32x16_bf16 v[96:111], v[168:171], v[152:155], v[96:111]
	v_mfma_f32_32x32x16_bf16 v[64:79], v[186:189], v[152:155], v[64:79]
	v_add_u32_e32 v186, s14, v218
	ds_read_b128 v[168:171], v186
	ds_read_b128 v[186:189], v186 offset:8192
	s_mov_b32 m0, s17
	s_add_u32 s100, s72, 0x26580000
	s_addc_u32 s101, s73, 0
	global_load_lds_dwordx4 v178, s[100:101]
	s_waitcnt lgkmcnt(0)
	v_mfma_f32_32x32x16_bf16 v[96:111], v[168:171], v[148:151], v[96:111]
	v_mfma_f32_32x32x16_bf16 v[64:79], v[186:189], v[148:151], v[64:79]
	v_add_u32_e32 v186, s14, v221
	ds_read_b128 v[168:171], v186
	ds_read_b128 v[186:189], v186 offset:8192
	s_waitcnt lgkmcnt(0)
	v_mfma_f32_32x32x16_bf16 v[96:111], v[168:171], v[144:147], v[96:111]
	v_mfma_f32_32x32x16_bf16 v[64:79], v[186:189], v[144:147], v[64:79]
	v_add_u32_e32 v186, s14, v222
	ds_read_b128 v[168:171], v186
	ds_read_b128 v[186:189], v186 offset:8192
	s_add_i32 m0, s17, 0x400
	s_nop 0
	global_load_lds_dwordx4 v180, s[100:101]
	v_exp_f32_e32 v190, v88
	s_waitcnt lgkmcnt(0)
	v_mfma_f32_32x32x16_bf16 v[96:111], v[168:171], v[140:143], v[96:111]
	v_mfma_f32_32x32x16_bf16 v[64:79], v[186:189], v[140:143], v[64:79]
	v_add_u32_e32 v186, s14, v223
	ds_read_b128 v[168:171], v186
	ds_read_b128 v[186:189], v186 offset:8192
	v_exp_f32_e32 v191, v89
	s_waitcnt lgkmcnt(0)
	v_mfma_f32_32x32x16_bf16 v[96:111], v[168:171], v[136:139], v[96:111]
	v_mfma_f32_32x32x16_bf16 v[64:79], v[186:189], v[136:139], v[64:79]
	v_add_u32_e32 v186, s14, v224
	ds_read_b128 v[168:171], v186
	ds_read_b128 v[186:189], v186 offset:8192
	s_mov_b32 m0, s15
	s_add_u32 s100, s72, 0x26580100
	s_addc_u32 s101, s73, 0
	global_load_lds_dwordx4 v176, s[100:101]
	v_exp_f32_e32 v192, v90
	s_waitcnt lgkmcnt(0)
	v_mfma_f32_32x32x16_bf16 v[96:111], v[168:171], v[132:135], v[96:111]
	v_mfma_f32_32x32x16_bf16 v[64:79], v[186:189], v[132:135], v[64:79]
	v_add_u32_e32 v186, s14, v225
	ds_read_b128 v[168:171], v186
	ds_read_b128 v[186:189], v186 offset:8192
	v_exp_f32_e32 v193, v91
	s_waitcnt lgkmcnt(0)
	v_mfma_f32_32x32x16_bf16 v[96:111], v[168:171], v[128:131], v[96:111]
	v_mfma_f32_32x32x16_bf16 v[64:79], v[186:189], v[128:131], v[64:79]
	v_add_u32_e32 v186, s14, v226
	ds_read_b128 v[168:171], v186 offset:16384
	ds_read_b128 v[186:189], v186 offset:20480
	s_add_i32 m0, s15, 0x400
	s_add_u32 s100, s72, 0x26580180
	s_addc_u32 s101, s73, 0
	global_load_lds_dwordx4 v176, s[100:101]
	v_exp_f32_e32 v241, v92
	s_waitcnt lgkmcnt(0)
	v_mfma_f32_32x32x16_bf16 v[96:111], v[168:171], v[124:127], v[96:111]
	v_mfma_f32_32x32x16_bf16 v[64:79], v[186:189], v[124:127], v[64:79]
	v_add_u32_e32 v186, s14, v227
	ds_read_b128 v[168:171], v186 offset:16384
	ds_read_b128 v[186:189], v186 offset:20480
	v_exp_f32_e32 v242, v93
	s_waitcnt lgkmcnt(0)
	v_mfma_f32_32x32x16_bf16 v[96:111], v[168:171], v[120:123], v[96:111]
	v_mfma_f32_32x32x16_bf16 v[64:79], v[186:189], v[120:123], v[64:79]
	v_add_u32_e32 v186, s14, v228
	ds_read_b128 v[168:171], v186 offset:16384
	ds_read_b128 v[186:189], v186 offset:20480
	s_add_i32 m0, s18, 0x4000
	s_add_u32 s100, s72, 0x21206000
	s_addc_u32 s101, s73, 0
	global_load_lds_dwordx4 v174, s[100:101]
	v_exp_f32_e32 v94, v94
	s_waitcnt lgkmcnt(0)
	v_mfma_f32_32x32x16_bf16 v[96:111], v[168:171], v[116:119], v[96:111]
	v_mfma_f32_32x32x16_bf16 v[64:79], v[186:189], v[116:119], v[64:79]
	v_add_u32_e32 v186, s14, v229
	ds_read_b128 v[168:171], v186 offset:16384
	ds_read_b128 v[186:189], v186 offset:20480
	v_exp_f32_e32 v95, v95
	s_waitcnt lgkmcnt(0)
; #define SBAR() __builtin_amdgcn_sched_barrier(0)
; __device__ __forceinline__ void finishSM(f32x16& p0, f32x16& p1, float alpha, float& l_reg, bf16x8& pa0, bf16x8& pa1, bf16x8& pa2, bf16x8& pa3) {
; #pragma unroll
;     for (int r = 0; r < 16; ++r) p1[r] = __builtin_amdgcn_exp2f(p1[r]);
;     float ps = 0;
; #pragma unroll
;     for (int r = 0; r < 16; ++r) ps += p0[r];
; #pragma unroll
;     for (int r = 0; r < 16; ++r) ps += p1[r];
;     { auto rr = __builtin_amdgcn_permlane32_swap(__float_as_uint(ps), __float_as_uint(ps), false, false);
;       ps = __uint_as_float(rr[0]) + __uint_as_float(rr[1]); }
;     l_reg = l_reg * alpha + ps;
;     ...
;     PK4(p0, 0, pa0); PK4(p0, 8, pa1); PK4(p1, 0, pa2); PK4(p1, 8, pa3);
; template <int D0> __device__ __forceinline__ void pv_one(f32x16& od, int vb, bf16x8 pa0, bf16x8 pa1, bf16x8 pa2, bf16x8 pa3) {
;     const s16x4 l0 = tr_read<v_rd_off(D0, 0, 0)>(vb), h0 = tr_read<v_rd_off(D0, 0, 1)>(vb), l1 = tr_read<v_rd_off(D0, 1, 0)>(vb), h1 = tr_read<v_rd_off(D0, 1, 1)>(vb);
;     const s16x4 l2 = tr_read<v_rd_off(D0, 2, 0)>(vb), h2 = tr_read<v_rd_off(D0, 2, 1)>(vb), l3 = tr_read<v_rd_off(D0, 3, 0)>(vb), h3 = tr_read<v_rd_off(D0, 3, 1)>(vb);
;     asm volatile("s_waitcnt lgkmcnt(0)" ::: "memory"); SBAR();
;     ...
;     od = __builtin_amdgcn_mfma_f32_32x32x16_bf16(pa0, PK(l0, h0), od, 0, 0, 0);
;     od = __builtin_amdgcn_mfma_f32_32x32x16_bf16(pa1, PK(l1, h1), od, 0, 0, 0);
;     od = __builtin_amdgcn_mfma_f32_32x32x16_bf16(pa2, PK(l2, h2), od, 0, 0, 0);
;     od = __builtin_amdgcn_mfma_f32_32x32x16_bf16(pa3, PK(l3, h3), od, 0, 0, 0);
;     ...
; }
; __device__ __forceinline__ void pv_d0(f32x16* o, int vb, bf16x8 pa0, bf16x8 pa1, bf16x8 pa2, bf16x8 pa3) {
;     pv_one<0>(o[0], vb, pa0, pa1, pa2, pa3); pv_one<1>(o[1], vb, pa0, pa1, pa2, pa3); pv_one<2>(o[2], vb, pa0, pa1, pa2, pa3); pv_one<3>(o[3], vb, pa0, pa1, pa2, pa3);
	v_mfma_f32_32x32x16_bf16 v[96:111], v[168:171], v[112:115], v[96:111]
	v_exp_f32_e32 v168, v80
	v_add_f32_e32 v80, 0, v172
	v_add_f32_e32 v80, v173, v80
	v_add_f32_e32 v80, v182, v80
	v_add_f32_e32 v80, v195, v80
	v_add_f32_e32 v80, v196, v80
	v_add_f32_e32 v80, v197, v80
	v_add_f32_e32 v80, v198, v80
	v_add_f32_e32 v80, v199, v80
	v_add_f32_e32 v80, v200, v80
	v_add_f32_e32 v80, v234, v80
	v_add_f32_e32 v80, v235, v80
	v_add_f32_e32 v80, v236, v80
	v_add_f32_e32 v80, v237, v80
	v_exp_f32_e32 v169, v81
	v_add_f32_e32 v80, v238, v80
	v_exp_f32_e32 v170, v82
	v_add_f32_e32 v80, v239, v80
	v_exp_f32_e32 v171, v83
	v_add_f32_e32 v80, v240, v80
	v_mfma_f32_32x32x16_bf16 v[64:79], v[186:189], v[112:115], v[64:79]
	v_exp_f32_e32 v186, v84
	v_add_f32_e32 v80, v168, v80
	v_exp_f32_e32 v187, v85
	v_add_f32_e32 v80, v169, v80
	v_exp_f32_e32 v188, v86
	v_add_f32_e32 v80, v170, v80
	v_exp_f32_e32 v189, v87
	v_add_f32_e32 v80, v171, v80
	v_add_f32_e32 v80, v186, v80
	v_add_f32_e32 v80, v187, v80
	v_add_f32_e32 v80, v188, v80
	v_add_f32_e32 v80, v189, v80
	v_add_f32_e32 v80, v190, v80
	v_add_f32_e32 v80, v191, v80
	v_add_f32_e32 v80, v192, v80
	v_add_f32_e32 v80, v193, v80
	v_add_f32_e32 v80, v241, v80
	v_add_f32_e32 v80, v242, v80
	v_add_f32_e32 v80, v94, v80
	v_add_f32_e32 v80, v95, v80
	v_mov_b32_e32 v81, v80
	v_cvt_pk_bf16_f32 v82, v172, v173
	v_cvt_pk_bf16_f32 v83, v182, v195
	v_cvt_pk_bf16_f32 v84, v196, v197
	s_nop 1
	v_permlane32_swap_b32_e32 v80, v81
	v_cvt_pk_bf16_f32 v85, v198, v199
	v_permlane32_swap_b32_e32 v82, v84
	v_cvt_pk_bf16_f32 v86, v200, v234
	v_cvt_pk_bf16_f32 v87, v235, v236
	v_cvt_pk_bf16_f32 v88, v237, v238
	v_cvt_pk_bf16_f32 v89, v239, v240
	v_cvt_pk_bf16_f32 v90, v168, v169
	v_cvt_pk_bf16_f32 v91, v170, v171
	v_cvt_pk_bf16_f32 v92, v186, v187
	v_cvt_pk_bf16_f32 v93, v188, v189
	v_cvt_pk_bf16_f32 v168, v190, v191
	v_cvt_pk_bf16_f32 v169, v192, v193
	v_cvt_pk_bf16_f32 v170, v241, v242
	v_cvt_pk_bf16_f32 v171, v94, v95
	v_permlane32_swap_b32_e32 v83, v85
	v_permlane32_swap_b32_e32 v86, v88
	v_permlane32_swap_b32_e32 v87, v89
	v_permlane32_swap_b32_e32 v90, v92
	v_permlane32_swap_b32_e32 v91, v93
	v_permlane32_swap_b32_e32 v168, v170
	v_permlane32_swap_b32_e32 v169, v171
	s_setprio 0
	v_lshl_add_u32 v94, s13, 14, v205
	ds_read_b64_tr_b16 v[186:187], v94 offset:0
	ds_read_b64_tr_b16 v[188:189], v94 offset:0x800
	ds_read_b64_tr_b16 v[190:191], v94 offset:0x1000
	ds_read_b64_tr_b16 v[192:193], v94 offset:0x1800
	ds_read_b64_tr_b16 v[196:197], v94 offset:0x2000
	ds_read_b64_tr_b16 v[198:199], v94 offset:0x2800
	ds_read_b64_tr_b16 v[234:235], v94 offset:0x3000
	ds_read_b64_tr_b16 v[236:237], v94 offset:0x3800
	s_waitcnt lgkmcnt(0)
	s_nop 0
	v_mfma_f32_32x32x16_bf16 v[0:15], v[82:85], v[186:189], v[0:15]
	ds_read_b64_tr_b16 v[186:187], v94 offset:0x200
	ds_read_b64_tr_b16 v[188:189], v94 offset:0xa00
	v_mfma_f32_32x32x16_bf16 v[0:15], v[86:89], v[190:193], v[0:15]
	ds_read_b64_tr_b16 v[190:191], v94 offset:0x1200
	ds_read_b64_tr_b16 v[192:193], v94 offset:0x1a00
	v_mfma_f32_32x32x16_bf16 v[0:15], v[90:93], v[196:199], v[0:15]
	ds_read_b64_tr_b16 v[196:197], v94 offset:0x2200
	ds_read_b64_tr_b16 v[198:199], v94 offset:0x2a00
	v_mfma_f32_32x32x16_bf16 v[0:15], v[168:171], v[234:237], v[0:15]
	ds_read_b64_tr_b16 v[234:235], v94 offset:0x3200
	ds_read_b64_tr_b16 v[236:237], v94 offset:0x3a00
	s_waitcnt lgkmcnt(0)
	v_mfma_f32_32x32x16_bf16 v[48:63], v[82:85], v[186:189], v[48:63]
	ds_read_b64_tr_b16 v[186:187], v94 offset:0x400
	ds_read_b64_tr_b16 v[188:189], v94 offset:0xc00
	v_mfma_f32_32x32x16_bf16 v[48:63], v[86:89], v[190:193], v[48:63]
	ds_read_b64_tr_b16 v[190:191], v94 offset:0x1400
	ds_read_b64_tr_b16 v[192:193], v94 offset:0x1c00
	v_mfma_f32_32x32x16_bf16 v[48:63], v[90:93], v[196:199], v[48:63]
	ds_read_b64_tr_b16 v[196:197], v94 offset:0x2400
	ds_read_b64_tr_b16 v[198:199], v94 offset:0x2c00
	v_mfma_f32_32x32x16_bf16 v[48:63], v[168:171], v[234:237], v[48:63]
	ds_read_b64_tr_b16 v[234:235], v94 offset:0x3400
	ds_read_b64_tr_b16 v[236:237], v94 offset:0x3c00
	s_waitcnt lgkmcnt(0)
	v_mfma_f32_32x32x16_bf16 v[32:47], v[82:85], v[186:189], v[32:47]
	ds_read_b64_tr_b16 v[186:187], v94 offset:0x600
	ds_read_b64_tr_b16 v[188:189], v94 offset:0xe00
	v_mfma_f32_32x32x16_bf16 v[32:47], v[86:89], v[190:193], v[32:47]
	ds_read_b64_tr_b16 v[190:191], v94 offset:0x1600
	ds_read_b64_tr_b16 v[192:193], v94 offset:0x1e00
	v_mfma_f32_32x32x16_bf16 v[32:47], v[90:93], v[196:199], v[32:47]
	ds_read_b64_tr_b16 v[196:197], v94 offset:0x2600
	ds_read_b64_tr_b16 v[198:199], v94 offset:0x2e00
	v_mfma_f32_32x32x16_bf16 v[32:47], v[168:171], v[234:237], v[32:47]
	ds_read_b64_tr_b16 v[234:235], v94 offset:0x3600
	ds_read_b64_tr_b16 v[236:237], v94 offset:0x3e00
	s_waitcnt lgkmcnt(0)
	v_mfma_f32_32x32x16_bf16 v[16:31], v[82:85], v[186:189], v[16:31]
	v_max_f32_e32 v82, v97, v97
	v_max_f32_e32 v83, v96, v96
	v_max_f32_e32 v82, v83, v82
	v_max3_f32 v82, v82, v98, v99
	v_max3_f32 v82, v82, v100, v101
	v_max3_f32 v82, v82, v102, v103
	v_max3_f32 v82, v82, v104, v105
	v_mfma_f32_32x32x16_bf16 v[16:31], v[86:89], v[190:193], v[16:31]
	v_max3_f32 v82, v82, v106, v107
	v_max3_f32 v82, v82, v108, v109
	v_max3_f32 v82, v82, v110, v111
	v_max3_f32 v82, v82, v64, v65
	v_max3_f32 v82, v82, v66, v67
	v_max3_f32 v82, v82, v68, v69
	v_max3_f32 v82, v82, v70, v71
	v_mfma_f32_32x32x16_bf16 v[16:31], v[90:93], v[196:199], v[16:31]
	v_max3_f32 v82, v82, v72, v73
	v_max3_f32 v82, v82, v74, v75
	v_max3_f32 v82, v82, v76, v77
	v_max3_f32 v82, v82, v78, v79
	v_mov_b32_e32 v83, v82
	s_nop 1
	v_permlane32_swap_b32_e32 v82, v83
	v_max_f32_e32 v83, v83, v83
	v_max_f32_e32 v82, v82, v82
	v_mfma_f32_32x32x16_bf16 v[16:31], v[168:171], v[234:237], v[16:31]
	v_max_f32_e32 v82, v82, v83
	v_sub_f32_e32 v83, v82, v184
	s_mov_b32 s0, 0x41300000
	v_cmp_ge_f32_e32 vcc, s0, v83
	s_cmp_eq_u64 vcc, exec
	v_max_f32_e32 v83, v184, v184
	s_cselect_b64 vcc, -1, 0
	v_max_f32_e32 v82, v83, v82
	v_cndmask_b32_e32 v182, v82, v184, vcc
	v_cmp_eq_f32_e64 s[0:1], 0, v182
	s_cmp_eq_u64 s[0:1], exec
	s_cbranch_scc0 .LBB0_229

; template <bool FIRST>
; __device__ __forceinline__ void partialSM(f32x16& p0, f32x16& p1, float& m_reg, float& mn, float& alpha) {
;     ...
;     for (int r = 0; r < 16; ++r) p0[r] = __builtin_amdgcn_exp2f(p0[r]);
; }
; __device__ __forceinline__ void finishSM(f32x16& p0, f32x16& p1, float alpha, float& l_reg, bf16x8& pa0, bf16x8& pa1, bf16x8& pa2, bf16x8& pa3) {
; #pragma unroll
;     for (int r = 0; r < 16; ++r) p1[r] = __builtin_amdgcn_exp2f(p1[r]);
;     float ps = 0;
; #pragma unroll
;     for (int r = 0; r < 16; ++r) ps += p0[r];
; #pragma unroll
;     for (int r = 0; r < 16; ++r) ps += p1[r];
;     { auto rr = __builtin_amdgcn_permlane32_swap(__float_as_uint(ps), __float_as_uint(ps), false, false);
;       ps = __uint_as_float(rr[0]) + __uint_as_float(rr[1]); }
;     l_reg = l_reg * alpha + ps;
.LBB0_226:
	v_exp_f32_e32 v247, v96
	v_exp_f32_e32 v249, v97
	v_exp_f32_e32 v245, v98
	v_exp_f32_e32 v248, v99
	v_exp_f32_e32 v244, v100
	v_exp_f32_e32 v246, v101
	v_exp_f32_e32 v242, v102
	v_exp_f32_e32 v243, v103
	v_exp_f32_e32 v239, v104
	v_exp_f32_e32 v241, v105
	v_exp_f32_e32 v238, v106
	v_exp_f32_e32 v240, v107
	v_exp_f32_e32 v235, v108
	v_exp_f32_e32 v237, v109
	v_exp_f32_e32 v234, v110
	v_exp_f32_e32 v236, v111
	v_add_f32_e32 v82, v231, v232
	s_mov_b64 s[0:1], 0x4000
	v_fmac_f32_e32 v82, v230, v203
	v_add_f32_e32 v203, v80, v81
	s_add_i32 s11, s11, 2
	v_lshl_add_u64 v[174:175], v[174:175], 0, s[0:1]
	s_mov_b64 s[0:1], 0x100000
	v_fmac_f32_e32 v203, v82, v233
	v_lshl_add_u64 v[176:177], v[176:177], 0, s[0:1]
	v_lshl_add_u64 v[178:179], v[178:179], 0, s[0:1]
	v_lshl_add_u64 v[180:181], v[180:181], 0, s[0:1]
	s_waitcnt vmcnt(0) lgkmcnt(0)
	s_barrier
	s_cmpk_gt_u32 s11, 0x7c
	s_cbranch_scc1 .LBB0_230
	s_mov_b32 s15, s9
	s_mov_b32 s9, s13
	v_mov_b32_e32 v230, v184
	s_branch .LBB0_216

; __device__ __forceinline__ float fsigmoid(float x) { return __builtin_amdgcn_rcpf(1.0f + __expf(-x)); }
;     __device__ __forceinline__ void operator()(const Acc& acc, const Unit& u, int wr, int wc, int fr, int fq) const {
;     ...
;                     for (int j = 0; j < 4; ++j) { const float r = fsigmoid(acc[ai][0][m][n][j] + ba[n][j]), ig = fsigmoid(acc[ai][1][m][n][j] + bi[n][j]);
;                         const float y = r * cc[n][j];
;                         float o1 = y * (1.0f - y * (0.5f - y * (0.16666667f - y * (0.041666668f - y * 0.008333334f))));
;                         if (__builtin_expect(__any(y >= 0.125f), 0)) { const float ome = 1.0f - __expf(-y); o1 = y < 0.125f ? o1 : ome; }
;                         om[n * 4 + j] = o1; uv[n * 4 + j] = sqrtf(o1 * (2.0f - o1)) * (ig * xv[n * 4 + j]); }
.LBB0_344:
	v_sub_f32_e32 v168, 2.0, v146
	v_mul_f32_e32 v168, v146, v168
	v_add_f32_e32 v142, v142, v42
	v_mul_f32_e32 v142, 0xbfb8aa3b, v142
	v_sqrt_f32_e32 v169, v168
	v_exp_f32_e32 v142, v142
	v_add_f32_e32 v143, v143, v43
	v_mul_f32_e32 v143, 0xbfb8aa3b, v143
	v_add_f32_e32 v142, 1.0, v142
	v_rcp_f32_e32 v142, v142
	v_exp_f32_e32 v143, v143
	v_lshlrev_b32_e32 v170, 16, v155
	v_mul_f32_e32 v142, v142, v170
	v_add_f32_e32 v141, v141, v41
	v_mov_b32_e32 v168, v169
	v_mul_f32_e32 v168, v142, v168
	v_add_f32_e32 v142, 1.0, v143
	v_sub_f32_e32 v143, 2.0, v145
	v_mul_f32_e32 v143, v145, v143
	v_mul_f32_e32 v141, 0xbfb8aa3b, v141
	v_exp_f32_e32 v141, v141
	v_sqrt_f32_e32 v169, v143
	v_and_b32_e32 v170, 0xffff0000, v154
	v_add_f32_e32 v141, 1.0, v141
	v_rcp_f32_e32 v141, v141
	s_nop 0
	v_mul_f32_e32 v141, v141, v170
	v_add_f32_e32 v140, v140, v40
	v_mul_f32_e32 v140, 0xbfb8aa3b, v140
	v_exp_f32_e32 v140, v140
	v_lshlrev_b32_e32 v154, 16, v154
	v_mov_b32_e32 v143, v169
	v_mul_f32_e32 v143, v141, v143
	v_sub_f32_e32 v141, 2.0, v144
	v_mul_f32_e32 v141, v144, v141
	v_add_f32_e32 v140, 1.0, v140
	v_rcp_f32_e32 v140, v140
	v_sqrt_f32_e32 v169, v141
	v_add_f32_e32 v139, v139, v35
	v_mul_f32_e32 v140, v140, v154
	v_mul_f32_e32 v139, 0xbfb8aa3b, v139
	v_exp_f32_e32 v139, v139
	s_nop 0
	v_add_f32_e32 v139, 1.0, v139
	v_rcp_f32_e32 v139, v139
	v_add_f32_e32 v138, v138, v34
	v_mul_f32_e32 v138, 0xbfb8aa3b, v138
	v_mov_b32_e32 v141, v169
	v_mul_f32_e32 v154, v140, v141
	v_sub_f32_e32 v140, 2.0, v151
	v_mul_f32_e32 v140, v151, v140
	v_and_b32_e32 v169, 0xffff0000, v153
	v_mul_f32_e32 v139, v139, v169
	v_sqrt_f32_e32 v141, v140
	v_exp_f32_e32 v138, v138
	v_lshlrev_b32_e32 v153, 16, v153
	v_add_f32_e32 v137, v137, v33
	v_add_f32_e32 v138, 1.0, v138
	v_rcp_f32_e32 v138, v138
	v_mul_f32_e32 v137, 0xbfb8aa3b, v137
	v_mul_f32_e32 v138, v138, v153
	v_exp_f32_e32 v137, v137
	v_mov_b32_e32 v140, v141
	v_mul_f32_e32 v141, v139, v140
	v_sub_f32_e32 v139, 2.0, v150
	v_mul_f32_e32 v139, v150, v139
	v_add_f32_e32 v137, 1.0, v137
	v_rcp_f32_e32 v137, v137
	v_sqrt_f32_e32 v140, v139
	v_add_f32_e32 v136, v136, v32
	v_mul_f32_e32 v136, 0xbfb8aa3b, v136
	v_exp_f32_e32 v136, v136
	s_nop 0
	v_add_f32_e32 v136, 1.0, v136
	v_rcp_f32_e32 v136, v136
	s_ashr_i32 s13, s12, 31
	v_rcp_f32_e32 v142, v142
	v_add_f32_e32 v132, v132, v64
	v_mov_b32_e32 v139, v140
	v_mul_f32_e32 v153, v138, v139
	v_sub_f32_e32 v138, 2.0, v149
	v_mul_f32_e32 v138, v149, v138
	v_and_b32_e32 v140, 0xffff0000, v152
	v_mul_f32_e32 v137, v137, v140
	v_sqrt_f32_e32 v139, v138
	v_mul_f32_e32 v132, 0xbfb8aa3b, v132
	v_exp_f32_e32 v132, v132
	s_nop 0
	v_add_f32_e32 v132, 1.0, v132
	v_rcp_f32_e32 v132, v132
	s_nop 0
	s_nop 1
	s_nop 0
	v_mov_b32_e32 v138, v139
	v_mul_f32_e32 v140, v137, v138
	v_sub_f32_e32 v137, 2.0, v148
	v_mul_f32_e32 v137, v148, v137
	v_lshlrev_b32_e32 v139, 16, v152
	v_mul_f32_e32 v136, v136, v139
	v_sqrt_f32_e32 v138, v137
	s_nop 0
	s_nop 0
	s_nop 1
	s_lshl_b64 s[0:1], s[12:13], 27
	v_readlane_b32 s12, v251, 42
	v_mov_b32_e32 v137, v138
	v_mul_f32_e32 v152, v136, v137
	v_sub_f32_e32 v136, 2.0, v147
	v_mul_f32_e32 v136, v147, v136
	v_readlane_b32 s13, v251, 43
	s_add_u32 s12, s12, s0
	v_sqrt_f32_e32 v137, v136
	s_addc_u32 s13, s13, s1
	s_add_u32 s16, s78, s0
	v_and_b32_e32 v138, 0xffff0000, v155
	s_addc_u32 s17, s79, s1
	s_nop 0
	s_nop 1
	s_mov_b64 s[0:1], 0x8000
	s_nop 0
	v_mov_b32_e32 v136, v137
	v_mul_f32_e32 v137, v142, v138
	v_mul_f32_e32 v155, v137, v136
	v_cvt_pk_bf16_f32 v136, v148, v149
	v_cvt_pk_bf16_f32 v137, v150, v151
	v_cvt_pk_bf16_f32 v138, v144, v145
	v_lshlrev_b64 v[144:145], 1, v[184:185]
	v_cvt_pk_bf16_f32 v139, v146, v147
	v_lshl_add_u64 v[146:147], s[12:13], 0, v[144:145]
	v_cvt_pk_bf16_f32 v140, v152, v140
	v_cvt_pk_bf16_f32 v141, v153, v141
	v_cvt_pk_bf16_f32 v142, v154, v143
	v_cvt_pk_bf16_f32 v143, v168, v155
	global_store_dwordx4 v[146:147], v[136:139], off
	s_nop 1
	v_lshl_add_u64 v[136:137], s[16:17], 0, v[144:145]
	global_store_dwordx4 v[136:137], v[140:143], off
	v_lshlrev_b64 v[136:137], 11, v[182:183]
	v_lshl_add_u64 v[136:137], v[136:137], 0, v[180:181]
	v_lshl_add_u64 v[140:141], v[136:137], 0, s[0:1]
	v_readlane_b32 s0, v252, 6
	v_readlane_b32 s1, v252, 7
	v_mul_f32_e32 v142, v68, v132
	v_fmamk_f32 v132, v142, 0xbc088889, v163
	v_lshl_add_u64 v[136:137], v[140:141], 1, s[0:1]
	global_load_dwordx4 v[136:139], v[136:137], off
	v_fma_f32 v132, -v142, v132, s5
	v_fma_f32 v132, -v142, v132, 0.5
	v_fma_f32 v132, -v142, v132, 1.0
	v_mul_f32_e32 v132, v142, v132
	v_cmp_le_f32_e32 vcc, s8, v142
	s_cbranch_vccnz .LBB0_412

; __device__ __forceinline__ float bf2f(unsigned b) { return __uint_as_float(b << 16); }
; __device__ __forceinline__ unsigned cvt_pk_bf16(float lo, float hi) { unsigned r; asm volatile("v_cvt_pk_bf16_f32 %0, %1, %2" : "=v"(r) : "v"(lo), "v"(hi)); return r; }
; __device__ __forceinline__ float fsigmoid(float x) { return __builtin_amdgcn_rcpf(1.0f + __expf(-x)); }
;     __device__ __forceinline__ void operator()(const Acc& acc, const Unit& u, int wr, int wc, int fr, int fq) const {
;     ...
;             for (int m = 0; m < 4; ++m) { const int row = row0 + ai * HALF + m * 16; const size_t off = (size_t)row * DM + ch0;
;                 const u32x4 xw = *(const u32x4*)(xc + off);
;                 const float xv[8] = {bf2f(xw.x & 0xffffu), bf2f(xw.x >> 16), bf2f(xw.y & 0xffffu), bf2f(xw.y >> 16), bf2f(xw.z & 0xffffu), bf2f(xw.z >> 16), bf2f(xw.w & 0xffffu), bf2f(xw.w >> 16)};
;                 float om[8], uv[8];
; #pragma unroll
;                 for (int n = 0; n < 2; ++n)
; #pragma unroll
;                     for (int j = 0; j < 4; ++j) { const float r = fsigmoid(acc[ai][0][m][n][j] + ba[n][j]), ig = fsigmoid(acc[ai][1][m][n][j] + bi[n][j]);
;                         const float y = r * cc[n][j];
;                         float o1 = y * (1.0f - y * (0.5f - y * (0.16666667f - y * (0.041666668f - y * 0.008333334f))));
;                         if (__builtin_expect(__any(y >= 0.125f), 0)) { const float ome = 1.0f - __expf(-y); o1 = y < 0.125f ? o1 : ome; }
;                         om[n * 4 + j] = o1; uv[n * 4 + j] = sqrtf(o1 * (2.0f - o1)) * (ig * xv[n * 4 + j]); }
;                 u32x4 wa, wu; wa.x = cvt_pk_bf16(om[0], om[1]); wa.y = cvt_pk_bf16(om[2], om[3]); wa.z = cvt_pk_bf16(om[4], om[5]); wa.w = cvt_pk_bf16(om[6], om[7]);
;                 wu.x = cvt_pk_bf16(uv[0], uv[1]); wu.y = cvt_pk_bf16(uv[2], uv[3]); wu.z = cvt_pk_bf16(uv[4], uv[5]); wu.w = cvt_pk_bf16(uv[6], uv[7]);
;                 *(u32x4*)(Ao + off) = wa; *(u32x4*)(Uo + off) = wu; asm volatile("" ::: "memory"); }
.LBB0_352:
	v_sub_f32_e32 v142, 2.0, v130
	v_mul_f32_e32 v142, v130, v142
	v_add_f32_e32 v126, v126, v42
	v_mul_f32_e32 v126, 0xbfb8aa3b, v126
	v_sqrt_f32_e32 v143, v142
	v_exp_f32_e32 v126, v126
	v_add_f32_e32 v127, v127, v43
	v_mul_f32_e32 v127, 0xbfb8aa3b, v127
	v_add_f32_e32 v126, 1.0, v126
	v_rcp_f32_e32 v126, v126
	v_exp_f32_e32 v127, v127
	s_waitcnt vmcnt(0)
	v_lshlrev_b32_e32 v144, 16, v139
	v_mul_f32_e32 v126, v126, v144
	v_add_f32_e32 v125, v125, v41
	v_mov_b32_e32 v142, v143
	v_mul_f32_e32 v142, v126, v142
	v_add_f32_e32 v126, 1.0, v127
	v_sub_f32_e32 v127, 2.0, v129
	v_mul_f32_e32 v127, v129, v127
	v_mul_f32_e32 v125, 0xbfb8aa3b, v125
	v_exp_f32_e32 v125, v125
	v_sqrt_f32_e32 v143, v127
	v_and_b32_e32 v144, 0xffff0000, v138
	v_add_f32_e32 v125, 1.0, v125
	v_rcp_f32_e32 v125, v125
	s_nop 0
	v_mul_f32_e32 v125, v125, v144
	v_add_f32_e32 v124, v124, v40
	v_mul_f32_e32 v124, 0xbfb8aa3b, v124
	v_exp_f32_e32 v124, v124
	v_lshlrev_b32_e32 v138, 16, v138
	v_mov_b32_e32 v127, v143
	v_mul_f32_e32 v127, v125, v127
	v_sub_f32_e32 v125, 2.0, v128
	v_mul_f32_e32 v125, v128, v125
	v_add_f32_e32 v124, 1.0, v124
	v_rcp_f32_e32 v124, v124
	v_sqrt_f32_e32 v143, v125
	v_add_f32_e32 v123, v123, v35
	v_mul_f32_e32 v124, v124, v138
	v_mul_f32_e32 v123, 0xbfb8aa3b, v123
	v_exp_f32_e32 v123, v123
	s_nop 0
	v_add_f32_e32 v123, 1.0, v123
	v_rcp_f32_e32 v123, v123
	v_add_f32_e32 v122, v122, v34
	v_mul_f32_e32 v122, 0xbfb8aa3b, v122
	v_mov_b32_e32 v125, v143
	v_mul_f32_e32 v138, v124, v125
	v_sub_f32_e32 v124, 2.0, v135
	v_mul_f32_e32 v124, v135, v124
	v_and_b32_e32 v143, 0xffff0000, v137
	v_mul_f32_e32 v123, v123, v143
	v_sqrt_f32_e32 v125, v124
	v_exp_f32_e32 v122, v122
	v_lshlrev_b32_e32 v137, 16, v137
	v_add_f32_e32 v121, v121, v33
	v_add_f32_e32 v122, 1.0, v122
	v_rcp_f32_e32 v122, v122
	v_mul_f32_e32 v121, 0xbfb8aa3b, v121
	v_mul_f32_e32 v122, v122, v137
	v_exp_f32_e32 v121, v121
	v_mov_b32_e32 v124, v125
	v_mul_f32_e32 v125, v123, v124
	v_sub_f32_e32 v123, 2.0, v134
	v_mul_f32_e32 v123, v134, v123
	v_add_f32_e32 v121, 1.0, v121
	v_rcp_f32_e32 v121, v121
	v_sqrt_f32_e32 v124, v123
	v_add_f32_e32 v120, v120, v32
	v_mul_f32_e32 v120, 0xbfb8aa3b, v120
	v_exp_f32_e32 v120, v120
	s_nop 0
	v_add_f32_e32 v120, 1.0, v120
	v_rcp_f32_e32 v120, v120
	v_rcp_f32_e32 v126, v126
	v_add_f32_e32 v116, v116, v64
	v_mul_f32_e32 v116, 0xbfb8aa3b, v116
	v_mov_b32_e32 v123, v124
	v_mul_f32_e32 v137, v122, v123
	v_sub_f32_e32 v122, 2.0, v133
	v_mul_f32_e32 v122, v133, v122
	v_and_b32_e32 v124, 0xffff0000, v136
	v_mul_f32_e32 v121, v121, v124
	v_sqrt_f32_e32 v123, v122
	v_exp_f32_e32 v116, v116
	s_nop 0
	v_add_f32_e32 v116, 1.0, v116
	v_rcp_f32_e32 v116, v116
	s_nop 0
	s_nop 1
	s_nop 0
	v_mov_b32_e32 v122, v123
	v_mul_f32_e32 v124, v121, v122
	v_sub_f32_e32 v121, 2.0, v132
	v_mul_f32_e32 v121, v132, v121
	v_lshlrev_b32_e32 v123, 16, v136
	v_mul_f32_e32 v120, v120, v123
	v_sqrt_f32_e32 v122, v121
	s_nop 0
	s_nop 0
	s_nop 1
	s_nop 1
	s_nop 0
	v_mov_b32_e32 v121, v122
	v_sub_f32_e32 v122, 2.0, v131
	v_mul_f32_e32 v122, v131, v122
	v_mul_f32_e32 v143, v120, v121
	v_and_b32_e32 v120, 0xffff0000, v139
	v_sqrt_f32_e32 v136, v122
	v_mul_f32_e32 v120, v126, v120
	s_nop 0
	s_nop 1
	s_mov_b64 s[0:1], 0x10000
	s_nop 0
	v_mov_b32_e32 v121, v136
	v_mul_f32_e32 v136, v120, v121
	v_cvt_pk_bf16_f32 v120, v132, v133
	v_cvt_pk_bf16_f32 v121, v134, v135
	v_cvt_pk_bf16_f32 v122, v128, v129
	v_lshlrev_b64 v[128:129], 1, v[140:141]
	v_cvt_pk_bf16_f32 v123, v130, v131
	v_lshl_add_u64 v[130:131], s[12:13], 0, v[128:129]
	v_cvt_pk_bf16_f32 v124, v143, v124
	v_cvt_pk_bf16_f32 v125, v137, v125
	v_cvt_pk_bf16_f32 v126, v138, v127
	v_cvt_pk_bf16_f32 v127, v142, v136
	global_store_dwordx4 v[130:131], v[120:123], off
	s_nop 1
	v_lshl_add_u64 v[120:121], s[16:17], 0, v[128:129]
	global_store_dwordx4 v[120:121], v[124:127], off
	v_lshlrev_b64 v[120:121], 11, v[182:183]
	v_lshl_add_u64 v[120:121], v[120:121], 0, v[180:181]
	v_lshl_add_u64 v[124:125], v[120:121], 0, s[0:1]
	v_readlane_b32 s0, v252, 6
	v_readlane_b32 s1, v252, 7
	v_mul_f32_e32 v126, v68, v116
	v_fmamk_f32 v116, v126, 0xbc088889, v163
	v_lshl_add_u64 v[120:121], v[124:125], 1, s[0:1]
	global_load_dwordx4 v[120:123], v[120:121], off
	v_fma_f32 v116, -v126, v116, s5
	v_fma_f32 v116, -v126, v116, 0.5
	v_fma_f32 v116, -v126, v116, 1.0
	v_mul_f32_e32 v116, v126, v116
	v_cmp_le_f32_e32 vcc, s8, v126
	s_cbranch_vccnz .LBB0_420

; __device__ __forceinline__ float bf2f(unsigned b) { return __uint_as_float(b << 16); }
; __device__ __forceinline__ unsigned cvt_pk_bf16(float lo, float hi) { unsigned r; asm volatile("v_cvt_pk_bf16_f32 %0, %1, %2" : "=v"(r) : "v"(lo), "v"(hi)); return r; }
; __device__ __forceinline__ float fsigmoid(float x) { return __builtin_amdgcn_rcpf(1.0f + __expf(-x)); }
;     __device__ __forceinline__ void operator()(const Acc& acc, const Unit& u, int wr, int wc, int fr, int fq) const {
;     ...
;             for (int m = 0; m < 4; ++m) { const int row = row0 + ai * HALF + m * 16; const size_t off = (size_t)row * DM + ch0;
;                 const u32x4 xw = *(const u32x4*)(xc + off);
;                 const float xv[8] = {bf2f(xw.x & 0xffffu), bf2f(xw.x >> 16), bf2f(xw.y & 0xffffu), bf2f(xw.y >> 16), bf2f(xw.z & 0xffffu), bf2f(xw.z >> 16), bf2f(xw.w & 0xffffu), bf2f(xw.w >> 16)};
;                 float om[8], uv[8];
; #pragma unroll
;                 for (int n = 0; n < 2; ++n)
; #pragma unroll
;                     for (int j = 0; j < 4; ++j) { const float r = fsigmoid(acc[ai][0][m][n][j] + ba[n][j]), ig = fsigmoid(acc[ai][1][m][n][j] + bi[n][j]);
;                         const float y = r * cc[n][j];
;                         float o1 = y * (1.0f - y * (0.5f - y * (0.16666667f - y * (0.041666668f - y * 0.008333334f))));
;                         if (__builtin_expect(__any(y >= 0.125f), 0)) { const float ome = 1.0f - __expf(-y); o1 = y < 0.125f ? o1 : ome; }
;                         om[n * 4 + j] = o1; uv[n * 4 + j] = sqrtf(o1 * (2.0f - o1)) * (ig * xv[n * 4 + j]); }
;                 u32x4 wa, wu; wa.x = cvt_pk_bf16(om[0], om[1]); wa.y = cvt_pk_bf16(om[2], om[3]); wa.z = cvt_pk_bf16(om[4], om[5]); wa.w = cvt_pk_bf16(om[6], om[7]);
;                 wu.x = cvt_pk_bf16(uv[0], uv[1]); wu.y = cvt_pk_bf16(uv[2], uv[3]); wu.z = cvt_pk_bf16(uv[4], uv[5]); wu.w = cvt_pk_bf16(uv[6], uv[7]);
;                 *(u32x4*)(Ao + off) = wa; *(u32x4*)(Uo + off) = wu; asm volatile("" ::: "memory"); }
.LBB0_360:
	v_sub_f32_e32 v126, 2.0, v114
	v_mul_f32_e32 v126, v114, v126
	v_add_f32_e32 v110, v110, v42
	v_mul_f32_e32 v110, 0xbfb8aa3b, v110
	v_sqrt_f32_e32 v127, v126
	v_exp_f32_e32 v110, v110
	v_add_f32_e32 v111, v111, v43
	v_mul_f32_e32 v111, 0xbfb8aa3b, v111
	v_add_f32_e32 v110, 1.0, v110
	v_rcp_f32_e32 v110, v110
	v_exp_f32_e32 v111, v111
	s_waitcnt vmcnt(0)
	v_lshlrev_b32_e32 v128, 16, v123
	v_mul_f32_e32 v110, v110, v128
	v_add_f32_e32 v109, v109, v41
	v_mov_b32_e32 v126, v127
	v_mul_f32_e32 v126, v110, v126
	v_add_f32_e32 v110, 1.0, v111
	v_sub_f32_e32 v111, 2.0, v113
	v_mul_f32_e32 v111, v113, v111
	v_mul_f32_e32 v109, 0xbfb8aa3b, v109
	v_exp_f32_e32 v109, v109
	v_sqrt_f32_e32 v127, v111
	v_and_b32_e32 v128, 0xffff0000, v122
	v_add_f32_e32 v109, 1.0, v109
	v_rcp_f32_e32 v109, v109
	s_nop 0
	v_mul_f32_e32 v109, v109, v128
	v_add_f32_e32 v108, v108, v40
	v_mul_f32_e32 v108, 0xbfb8aa3b, v108
	v_exp_f32_e32 v108, v108
	v_lshlrev_b32_e32 v122, 16, v122
	v_mov_b32_e32 v111, v127
	v_mul_f32_e32 v111, v109, v111
	v_sub_f32_e32 v109, 2.0, v112
	v_mul_f32_e32 v109, v112, v109
	v_add_f32_e32 v108, 1.0, v108
	v_rcp_f32_e32 v108, v108
	v_sqrt_f32_e32 v127, v109
	v_add_f32_e32 v107, v107, v35
	v_mul_f32_e32 v108, v108, v122
	v_mul_f32_e32 v107, 0xbfb8aa3b, v107
	v_exp_f32_e32 v107, v107
	s_nop 0
	v_add_f32_e32 v107, 1.0, v107
	v_rcp_f32_e32 v107, v107
	v_add_f32_e32 v106, v106, v34
	v_mul_f32_e32 v106, 0xbfb8aa3b, v106
	v_mov_b32_e32 v109, v127
	v_mul_f32_e32 v122, v108, v109
	v_sub_f32_e32 v108, 2.0, v119
	v_mul_f32_e32 v108, v119, v108
	v_and_b32_e32 v127, 0xffff0000, v121
	v_mul_f32_e32 v107, v107, v127
	v_sqrt_f32_e32 v109, v108
	v_exp_f32_e32 v106, v106
	v_lshlrev_b32_e32 v121, 16, v121
	v_add_f32_e32 v105, v105, v33
	v_add_f32_e32 v106, 1.0, v106
	v_rcp_f32_e32 v106, v106
	v_mul_f32_e32 v105, 0xbfb8aa3b, v105
	v_mul_f32_e32 v106, v106, v121
	v_exp_f32_e32 v105, v105
	v_mov_b32_e32 v108, v109
	v_mul_f32_e32 v109, v107, v108
	v_sub_f32_e32 v107, 2.0, v118
	v_mul_f32_e32 v107, v118, v107
	v_add_f32_e32 v105, 1.0, v105
	v_rcp_f32_e32 v105, v105
	v_sqrt_f32_e32 v108, v107
	v_add_f32_e32 v104, v104, v32
	v_mul_f32_e32 v104, 0xbfb8aa3b, v104
	v_exp_f32_e32 v104, v104
	s_nop 0
	v_add_f32_e32 v104, 1.0, v104
	v_rcp_f32_e32 v104, v104
	v_rcp_f32_e32 v110, v110
	v_add_f32_e32 v100, v100, v64
	v_mul_f32_e32 v100, 0xbfb8aa3b, v100
	v_mov_b32_e32 v107, v108
	v_mul_f32_e32 v121, v106, v107
	v_sub_f32_e32 v106, 2.0, v117
	v_mul_f32_e32 v106, v117, v106
	v_and_b32_e32 v108, 0xffff0000, v120
	v_mul_f32_e32 v105, v105, v108
	v_sqrt_f32_e32 v107, v106
	v_exp_f32_e32 v100, v100
	s_nop 0
	v_add_f32_e32 v100, 1.0, v100
	v_rcp_f32_e32 v100, v100
	s_nop 0
	s_nop 1
	s_nop 0
	v_mov_b32_e32 v106, v107
	v_mul_f32_e32 v108, v105, v106
	v_sub_f32_e32 v105, 2.0, v116
	v_mul_f32_e32 v105, v116, v105
	v_lshlrev_b32_e32 v107, 16, v120
	v_mul_f32_e32 v104, v104, v107
	v_sqrt_f32_e32 v106, v105
	s_nop 0
	s_nop 0
	s_nop 1
	s_nop 1
	s_nop 0
	v_mov_b32_e32 v105, v106
	v_sub_f32_e32 v106, 2.0, v115
	v_mul_f32_e32 v106, v115, v106
	v_mul_f32_e32 v127, v104, v105
	v_and_b32_e32 v104, 0xffff0000, v123
	v_sqrt_f32_e32 v120, v106
	v_mul_f32_e32 v104, v110, v104
	s_nop 0
	s_nop 1
	s_mov_b64 s[0:1], 0x18000
	s_nop 0
	v_mov_b32_e32 v105, v120
	v_mul_f32_e32 v120, v104, v105
	v_cvt_pk_bf16_f32 v104, v116, v117
	v_cvt_pk_bf16_f32 v105, v118, v119
	v_cvt_pk_bf16_f32 v106, v112, v113
	v_lshlrev_b64 v[112:113], 1, v[124:125]
	v_cvt_pk_bf16_f32 v107, v114, v115
	v_lshl_add_u64 v[114:115], s[12:13], 0, v[112:113]
	v_cvt_pk_bf16_f32 v108, v127, v108
	v_cvt_pk_bf16_f32 v109, v121, v109
	v_cvt_pk_bf16_f32 v110, v122, v111
	v_cvt_pk_bf16_f32 v111, v126, v120
	global_store_dwordx4 v[114:115], v[104:107], off
	s_nop 1
	v_lshl_add_u64 v[104:105], s[16:17], 0, v[112:113]
	global_store_dwordx4 v[104:105], v[108:111], off
	v_lshlrev_b64 v[104:105], 11, v[182:183]
	v_lshl_add_u64 v[104:105], v[104:105], 0, v[180:181]
	v_lshl_add_u64 v[108:109], v[104:105], 0, s[0:1]
	v_readlane_b32 s0, v252, 6
	v_readlane_b32 s1, v252, 7
	v_mul_f32_e32 v110, v68, v100
	v_fmamk_f32 v100, v110, 0xbc088889, v163
	v_lshl_add_u64 v[104:105], v[108:109], 1, s[0:1]
	global_load_dwordx4 v[104:107], v[104:105], off
	v_fma_f32 v100, -v110, v100, s5
	v_fma_f32 v100, -v110, v100, 0.5
	v_fma_f32 v100, -v110, v100, 1.0
	v_mul_f32_e32 v100, v110, v100
	v_cmp_le_f32_e32 vcc, s8, v110
	s_cbranch_vccnz .LBB0_428

; __device__ __forceinline__ float bf2f(unsigned b) { return __uint_as_float(b << 16); }
; __device__ __forceinline__ unsigned cvt_pk_bf16(float lo, float hi) { unsigned r; asm volatile("v_cvt_pk_bf16_f32 %0, %1, %2" : "=v"(r) : "v"(lo), "v"(hi)); return r; }
; __device__ __forceinline__ float fsigmoid(float x) { return __builtin_amdgcn_rcpf(1.0f + __expf(-x)); }
;     __device__ __forceinline__ void operator()(const Acc& acc, const Unit& u, int wr, int wc, int fr, int fq) const {
;     ...
;             for (int m = 0; m < 4; ++m) { const int row = row0 + ai * HALF + m * 16; const size_t off = (size_t)row * DM + ch0;
;                 const u32x4 xw = *(const u32x4*)(xc + off);
;                 const float xv[8] = {bf2f(xw.x & 0xffffu), bf2f(xw.x >> 16), bf2f(xw.y & 0xffffu), bf2f(xw.y >> 16), bf2f(xw.z & 0xffffu), bf2f(xw.z >> 16), bf2f(xw.w & 0xffffu), bf2f(xw.w >> 16)};
;                 float om[8], uv[8];
; #pragma unroll
;                 for (int n = 0; n < 2; ++n)
; #pragma unroll
;                     for (int j = 0; j < 4; ++j) { const float r = fsigmoid(acc[ai][0][m][n][j] + ba[n][j]), ig = fsigmoid(acc[ai][1][m][n][j] + bi[n][j]);
;                         const float y = r * cc[n][j];
;                         float o1 = y * (1.0f - y * (0.5f - y * (0.16666667f - y * (0.041666668f - y * 0.008333334f))));
;                         if (__builtin_expect(__any(y >= 0.125f), 0)) { const float ome = 1.0f - __expf(-y); o1 = y < 0.125f ? o1 : ome; }
;                         om[n * 4 + j] = o1; uv[n * 4 + j] = sqrtf(o1 * (2.0f - o1)) * (ig * xv[n * 4 + j]); }
;                 u32x4 wa, wu; wa.x = cvt_pk_bf16(om[0], om[1]); wa.y = cvt_pk_bf16(om[2], om[3]); wa.z = cvt_pk_bf16(om[4], om[5]); wa.w = cvt_pk_bf16(om[6], om[7]);
;                 wu.x = cvt_pk_bf16(uv[0], uv[1]); wu.y = cvt_pk_bf16(uv[2], uv[3]); wu.z = cvt_pk_bf16(uv[4], uv[5]); wu.w = cvt_pk_bf16(uv[6], uv[7]);
;                 *(u32x4*)(Ao + off) = wa; *(u32x4*)(Uo + off) = wu; asm volatile("" ::: "memory"); }
.LBB0_368:
	v_sub_f32_e32 v110, 2.0, v98
	v_mul_f32_e32 v110, v98, v110
	v_add_f32_e32 v94, v94, v42
	v_mul_f32_e32 v94, 0xbfb8aa3b, v94
	v_sqrt_f32_e32 v111, v110
	v_exp_f32_e32 v94, v94
	v_add_f32_e32 v95, v95, v43
	v_mul_f32_e32 v95, 0xbfb8aa3b, v95
	v_add_f32_e32 v94, 1.0, v94
	v_rcp_f32_e32 v94, v94
	v_exp_f32_e32 v95, v95
	s_waitcnt vmcnt(0)
	v_lshlrev_b32_e32 v112, 16, v107
	v_mul_f32_e32 v94, v94, v112
	v_add_f32_e32 v93, v93, v41
	v_mov_b32_e32 v110, v111
	v_mul_f32_e32 v110, v94, v110
	v_add_f32_e32 v94, 1.0, v95
	v_sub_f32_e32 v95, 2.0, v97
	v_mul_f32_e32 v95, v97, v95
	v_mul_f32_e32 v93, 0xbfb8aa3b, v93
	v_exp_f32_e32 v93, v93
	v_sqrt_f32_e32 v111, v95
	v_and_b32_e32 v112, 0xffff0000, v106
	v_add_f32_e32 v93, 1.0, v93
	v_rcp_f32_e32 v93, v93
	s_nop 0
	v_mul_f32_e32 v93, v93, v112
	v_add_f32_e32 v92, v92, v40
	v_mul_f32_e32 v92, 0xbfb8aa3b, v92
	v_exp_f32_e32 v92, v92
	v_lshlrev_b32_e32 v106, 16, v106
	v_mov_b32_e32 v95, v111
	v_mul_f32_e32 v95, v93, v95
	v_sub_f32_e32 v93, 2.0, v96
	v_mul_f32_e32 v93, v96, v93
	v_add_f32_e32 v92, 1.0, v92
	v_rcp_f32_e32 v92, v92
	v_sqrt_f32_e32 v111, v93
	v_add_f32_e32 v91, v91, v35
	v_mul_f32_e32 v92, v92, v106
	v_mul_f32_e32 v91, 0xbfb8aa3b, v91
	v_exp_f32_e32 v91, v91
	s_nop 0
	v_add_f32_e32 v91, 1.0, v91
	v_rcp_f32_e32 v91, v91
	v_add_f32_e32 v90, v90, v34
	v_mul_f32_e32 v90, 0xbfb8aa3b, v90
	v_mov_b32_e32 v93, v111
	v_mul_f32_e32 v106, v92, v93
	v_sub_f32_e32 v92, 2.0, v103
	v_mul_f32_e32 v92, v103, v92
	v_and_b32_e32 v111, 0xffff0000, v105
	v_mul_f32_e32 v91, v91, v111
	v_sqrt_f32_e32 v93, v92
	v_exp_f32_e32 v90, v90
	v_lshlrev_b32_e32 v105, 16, v105
	v_add_f32_e32 v89, v89, v33
	v_add_f32_e32 v90, 1.0, v90
	v_rcp_f32_e32 v90, v90
	v_mul_f32_e32 v89, 0xbfb8aa3b, v89
	v_mul_f32_e32 v90, v90, v105
	v_exp_f32_e32 v89, v89
	v_mov_b32_e32 v92, v93
	v_mul_f32_e32 v93, v91, v92
	v_sub_f32_e32 v91, 2.0, v102
	v_mul_f32_e32 v91, v102, v91
	v_add_f32_e32 v89, 1.0, v89
	v_rcp_f32_e32 v89, v89
	v_sqrt_f32_e32 v92, v91
	v_add_f32_e32 v88, v88, v32
	v_mul_f32_e32 v88, 0xbfb8aa3b, v88
	v_exp_f32_e32 v88, v88
	s_nop 0
	v_add_f32_e32 v88, 1.0, v88
	v_rcp_f32_e32 v88, v88
	v_rcp_f32_e32 v94, v94
	v_add_f32_e32 v84, v84, v64
	v_mul_f32_e32 v84, 0xbfb8aa3b, v84
	v_mov_b32_e32 v91, v92
	v_mul_f32_e32 v105, v90, v91
	v_sub_f32_e32 v90, 2.0, v101
	v_mul_f32_e32 v90, v101, v90
	v_and_b32_e32 v92, 0xffff0000, v104
	v_mul_f32_e32 v89, v89, v92
	v_sqrt_f32_e32 v91, v90
	v_exp_f32_e32 v84, v84
	s_nop 0
	v_add_f32_e32 v84, 1.0, v84
	v_rcp_f32_e32 v84, v84
	s_nop 0
	s_nop 1
	s_nop 0
	v_mov_b32_e32 v90, v91
	v_mul_f32_e32 v92, v89, v90
	v_sub_f32_e32 v89, 2.0, v100
	v_mul_f32_e32 v89, v100, v89
	v_lshlrev_b32_e32 v91, 16, v104
	v_mul_f32_e32 v88, v88, v91
	v_sqrt_f32_e32 v90, v89
	s_nop 0
	s_nop 0
	s_nop 1
	s_nop 1
	s_nop 0
	v_mov_b32_e32 v89, v90
	v_sub_f32_e32 v90, 2.0, v99
	v_mul_f32_e32 v90, v99, v90
	v_mul_f32_e32 v111, v88, v89
	v_and_b32_e32 v88, 0xffff0000, v107
	v_sqrt_f32_e32 v104, v90
	v_mul_f32_e32 v88, v94, v88
	s_nop 0
	s_nop 1
	s_mov_b64 s[0:1], 0x40000
	s_nop 0
	v_mov_b32_e32 v89, v104
	v_mul_f32_e32 v104, v88, v89
	v_cvt_pk_bf16_f32 v88, v100, v101
	v_cvt_pk_bf16_f32 v89, v102, v103
	v_cvt_pk_bf16_f32 v90, v96, v97
	v_lshlrev_b64 v[96:97], 1, v[108:109]
	v_cvt_pk_bf16_f32 v91, v98, v99
	v_lshl_add_u64 v[98:99], s[12:13], 0, v[96:97]
	v_cvt_pk_bf16_f32 v92, v111, v92
	v_cvt_pk_bf16_f32 v93, v105, v93
	v_cvt_pk_bf16_f32 v94, v106, v95
	v_cvt_pk_bf16_f32 v95, v110, v104
	global_store_dwordx4 v[98:99], v[88:91], off
	s_nop 1
	v_lshl_add_u64 v[88:89], s[16:17], 0, v[96:97]
	global_store_dwordx4 v[88:89], v[92:95], off
	v_lshlrev_b64 v[88:89], 11, v[182:183]
	v_lshl_add_u64 v[88:89], v[88:89], 0, v[180:181]
	v_lshl_add_u64 v[92:93], v[88:89], 0, s[0:1]
	v_readlane_b32 s0, v252, 6
	v_readlane_b32 s1, v252, 7
	v_mul_f32_e32 v94, v68, v84
	v_fmamk_f32 v84, v94, 0xbc088889, v163
	v_lshl_add_u64 v[88:89], v[92:93], 1, s[0:1]
	global_load_dwordx4 v[88:91], v[88:89], off
	v_fma_f32 v84, -v94, v84, s5
	v_fma_f32 v84, -v94, v84, 0.5
	v_fma_f32 v84, -v94, v84, 1.0
	v_mul_f32_e32 v84, v94, v84
	v_cmp_le_f32_e32 vcc, s8, v94
	s_cbranch_vccnz .LBB0_436

; __device__ __forceinline__ float bf2f(unsigned b) { return __uint_as_float(b << 16); }
; __device__ __forceinline__ unsigned cvt_pk_bf16(float lo, float hi) { unsigned r; asm volatile("v_cvt_pk_bf16_f32 %0, %1, %2" : "=v"(r) : "v"(lo), "v"(hi)); return r; }
; __device__ __forceinline__ float fsigmoid(float x) { return __builtin_amdgcn_rcpf(1.0f + __expf(-x)); }
;     __device__ __forceinline__ void operator()(const Acc& acc, const Unit& u, int wr, int wc, int fr, int fq) const {
;     ...
;             for (int m = 0; m < 4; ++m) { const int row = row0 + ai * HALF + m * 16; const size_t off = (size_t)row * DM + ch0;
;                 const u32x4 xw = *(const u32x4*)(xc + off);
;                 const float xv[8] = {bf2f(xw.x & 0xffffu), bf2f(xw.x >> 16), bf2f(xw.y & 0xffffu), bf2f(xw.y >> 16), bf2f(xw.z & 0xffffu), bf2f(xw.z >> 16), bf2f(xw.w & 0xffffu), bf2f(xw.w >> 16)};
;                 float om[8], uv[8];
; #pragma unroll
;                 for (int n = 0; n < 2; ++n)
; #pragma unroll
;                     for (int j = 0; j < 4; ++j) { const float r = fsigmoid(acc[ai][0][m][n][j] + ba[n][j]), ig = fsigmoid(acc[ai][1][m][n][j] + bi[n][j]);
;                         const float y = r * cc[n][j];
;                         float o1 = y * (1.0f - y * (0.5f - y * (0.16666667f - y * (0.041666668f - y * 0.008333334f))));
;                         if (__builtin_expect(__any(y >= 0.125f), 0)) { const float ome = 1.0f - __expf(-y); o1 = y < 0.125f ? o1 : ome; }
;                         om[n * 4 + j] = o1; uv[n * 4 + j] = sqrtf(o1 * (2.0f - o1)) * (ig * xv[n * 4 + j]); }
;                 u32x4 wa, wu; wa.x = cvt_pk_bf16(om[0], om[1]); wa.y = cvt_pk_bf16(om[2], om[3]); wa.z = cvt_pk_bf16(om[4], om[5]); wa.w = cvt_pk_bf16(om[6], om[7]);
;                 wu.x = cvt_pk_bf16(uv[0], uv[1]); wu.y = cvt_pk_bf16(uv[2], uv[3]); wu.z = cvt_pk_bf16(uv[4], uv[5]); wu.w = cvt_pk_bf16(uv[6], uv[7]);
;                 *(u32x4*)(Ao + off) = wa; *(u32x4*)(Uo + off) = wu; asm volatile("" ::: "memory"); }
.LBB0_376:
	v_sub_f32_e32 v94, 2.0, v82
	v_mul_f32_e32 v94, v82, v94
	v_add_f32_e32 v78, v78, v42
	v_mul_f32_e32 v78, 0xbfb8aa3b, v78
	v_sqrt_f32_e32 v95, v94
	v_exp_f32_e32 v78, v78
	v_add_f32_e32 v79, v79, v43
	v_mul_f32_e32 v79, 0xbfb8aa3b, v79
	v_add_f32_e32 v78, 1.0, v78
	v_rcp_f32_e32 v78, v78
	v_exp_f32_e32 v79, v79
	s_waitcnt vmcnt(0)
	v_lshlrev_b32_e32 v96, 16, v91
	v_mul_f32_e32 v78, v78, v96
	v_add_f32_e32 v77, v77, v41
	v_mov_b32_e32 v94, v95
	v_mul_f32_e32 v94, v78, v94
	v_add_f32_e32 v78, 1.0, v79
	v_sub_f32_e32 v79, 2.0, v81
	v_mul_f32_e32 v79, v81, v79
	v_mul_f32_e32 v77, 0xbfb8aa3b, v77
	v_exp_f32_e32 v77, v77
	v_sqrt_f32_e32 v95, v79
	v_and_b32_e32 v96, 0xffff0000, v90
	v_add_f32_e32 v77, 1.0, v77
	v_rcp_f32_e32 v77, v77
	s_nop 0
	v_mul_f32_e32 v77, v77, v96
	v_add_f32_e32 v76, v76, v40
	v_mul_f32_e32 v76, 0xbfb8aa3b, v76
	v_exp_f32_e32 v76, v76
	v_lshlrev_b32_e32 v90, 16, v90
	v_mov_b32_e32 v79, v95
	v_mul_f32_e32 v79, v77, v79
	v_sub_f32_e32 v77, 2.0, v80
	v_mul_f32_e32 v77, v80, v77
	v_add_f32_e32 v76, 1.0, v76
	v_rcp_f32_e32 v76, v76
	v_sqrt_f32_e32 v95, v77
	v_add_f32_e32 v75, v75, v35
	v_mul_f32_e32 v76, v76, v90
	v_mul_f32_e32 v75, 0xbfb8aa3b, v75
	v_exp_f32_e32 v75, v75
	s_nop 0
	v_add_f32_e32 v75, 1.0, v75
	v_rcp_f32_e32 v75, v75
	v_add_f32_e32 v74, v74, v34
	v_mul_f32_e32 v74, 0xbfb8aa3b, v74
	v_mov_b32_e32 v77, v95
	v_mul_f32_e32 v90, v76, v77
	v_sub_f32_e32 v76, 2.0, v87
	v_mul_f32_e32 v76, v87, v76
	v_and_b32_e32 v95, 0xffff0000, v89
	v_mul_f32_e32 v75, v75, v95
	v_sqrt_f32_e32 v77, v76
	v_exp_f32_e32 v74, v74
	v_lshlrev_b32_e32 v89, 16, v89
	v_add_f32_e32 v73, v73, v33
	v_add_f32_e32 v74, 1.0, v74
	v_rcp_f32_e32 v74, v74
	v_mul_f32_e32 v73, 0xbfb8aa3b, v73
	v_mul_f32_e32 v74, v74, v89
	v_exp_f32_e32 v73, v73
	v_mov_b32_e32 v76, v77
	v_mul_f32_e32 v77, v75, v76
	v_sub_f32_e32 v75, 2.0, v86
	v_mul_f32_e32 v75, v86, v75
	v_add_f32_e32 v73, 1.0, v73
	v_rcp_f32_e32 v73, v73
	v_sqrt_f32_e32 v76, v75
	v_add_f32_e32 v72, v72, v32
	v_mul_f32_e32 v72, 0xbfb8aa3b, v72
	v_exp_f32_e32 v72, v72
	s_nop 0
	v_add_f32_e32 v72, 1.0, v72
	v_rcp_f32_e32 v72, v72
	v_rcp_f32_e32 v78, v78
	v_add_f32_e32 v60, v60, v64
	v_mul_f32_e32 v60, 0xbfb8aa3b, v60
	v_mov_b32_e32 v75, v76
	v_mul_f32_e32 v89, v74, v75
	v_sub_f32_e32 v74, 2.0, v85
	v_mul_f32_e32 v74, v85, v74
	v_and_b32_e32 v76, 0xffff0000, v88
	v_mul_f32_e32 v73, v73, v76
	v_sqrt_f32_e32 v75, v74
	v_exp_f32_e32 v60, v60
	s_nop 0
	v_add_f32_e32 v60, 1.0, v60
	v_rcp_f32_e32 v60, v60
	s_nop 0
	s_nop 1
	s_nop 0
	v_mov_b32_e32 v74, v75
	v_mul_f32_e32 v76, v73, v74
	v_sub_f32_e32 v73, 2.0, v84
	v_mul_f32_e32 v73, v84, v73
	v_lshlrev_b32_e32 v75, 16, v88
	v_mul_f32_e32 v72, v72, v75
	v_sqrt_f32_e32 v74, v73
	s_nop 0
	s_nop 0
	s_nop 1
	s_nop 1
	s_nop 0
	v_mov_b32_e32 v73, v74
	v_sub_f32_e32 v74, 2.0, v83
	v_mul_f32_e32 v74, v83, v74
	v_mul_f32_e32 v95, v72, v73
	v_and_b32_e32 v72, 0xffff0000, v91
	v_sqrt_f32_e32 v88, v74
	v_mul_f32_e32 v72, v78, v72
	s_nop 0
	s_nop 1
	s_mov_b64 s[0:1], 0x48000
	s_nop 0
	v_mov_b32_e32 v73, v88
	v_mul_f32_e32 v88, v72, v73
	v_cvt_pk_bf16_f32 v72, v84, v85
	v_cvt_pk_bf16_f32 v73, v86, v87
	v_cvt_pk_bf16_f32 v74, v80, v81
	v_lshlrev_b64 v[80:81], 1, v[92:93]
	v_cvt_pk_bf16_f32 v75, v82, v83
	v_lshl_add_u64 v[82:83], s[12:13], 0, v[80:81]
	v_cvt_pk_bf16_f32 v76, v95, v76
	v_cvt_pk_bf16_f32 v77, v89, v77
	v_cvt_pk_bf16_f32 v78, v90, v79
	v_cvt_pk_bf16_f32 v79, v94, v88
	global_store_dwordx4 v[82:83], v[72:75], off
	s_nop 1
	v_lshl_add_u64 v[72:73], s[16:17], 0, v[80:81]
	global_store_dwordx4 v[72:73], v[76:79], off
	v_lshlrev_b64 v[72:73], 11, v[182:183]
	v_lshl_add_u64 v[72:73], v[72:73], 0, v[180:181]
	v_lshl_add_u64 v[76:77], v[72:73], 0, s[0:1]
	v_readlane_b32 s0, v252, 6
	v_readlane_b32 s1, v252, 7
	v_mul_f32_e32 v78, v68, v60
	v_fmamk_f32 v60, v78, 0xbc088889, v163
	v_lshl_add_u64 v[72:73], v[76:77], 1, s[0:1]
	global_load_dwordx4 v[72:75], v[72:73], off
	v_fma_f32 v60, -v78, v60, s5
	v_fma_f32 v60, -v78, v60, 0.5
	v_fma_f32 v60, -v78, v60, 1.0
	v_mul_f32_e32 v60, v78, v60
	v_cmp_le_f32_e32 vcc, s8, v78
	s_cbranch_vccnz .LBB0_444

; __device__ __forceinline__ float bf2f(unsigned b) { return __uint_as_float(b << 16); }
; __device__ __forceinline__ unsigned cvt_pk_bf16(float lo, float hi) { unsigned r; asm volatile("v_cvt_pk_bf16_f32 %0, %1, %2" : "=v"(r) : "v"(lo), "v"(hi)); return r; }
; __device__ __forceinline__ float fsigmoid(float x) { return __builtin_amdgcn_rcpf(1.0f + __expf(-x)); }
;     __device__ __forceinline__ void operator()(const Acc& acc, const Unit& u, int wr, int wc, int fr, int fq) const {
;     ...
;             for (int m = 0; m < 4; ++m) { const int row = row0 + ai * HALF + m * 16; const size_t off = (size_t)row * DM + ch0;
;                 const u32x4 xw = *(const u32x4*)(xc + off);
;                 const float xv[8] = {bf2f(xw.x & 0xffffu), bf2f(xw.x >> 16), bf2f(xw.y & 0xffffu), bf2f(xw.y >> 16), bf2f(xw.z & 0xffffu), bf2f(xw.z >> 16), bf2f(xw.w & 0xffffu), bf2f(xw.w >> 16)};
;                 float om[8], uv[8];
; #pragma unroll
;                 for (int n = 0; n < 2; ++n)
; #pragma unroll
;                     for (int j = 0; j < 4; ++j) { const float r = fsigmoid(acc[ai][0][m][n][j] + ba[n][j]), ig = fsigmoid(acc[ai][1][m][n][j] + bi[n][j]);
;                         const float y = r * cc[n][j];
;                         float o1 = y * (1.0f - y * (0.5f - y * (0.16666667f - y * (0.041666668f - y * 0.008333334f))));
;                         if (__builtin_expect(__any(y >= 0.125f), 0)) { const float ome = 1.0f - __expf(-y); o1 = y < 0.125f ? o1 : ome; }
;                         om[n * 4 + j] = o1; uv[n * 4 + j] = sqrtf(o1 * (2.0f - o1)) * (ig * xv[n * 4 + j]); }
;                 u32x4 wa, wu; wa.x = cvt_pk_bf16(om[0], om[1]); wa.y = cvt_pk_bf16(om[2], om[3]); wa.z = cvt_pk_bf16(om[4], om[5]); wa.w = cvt_pk_bf16(om[6], om[7]);
;                 wu.x = cvt_pk_bf16(uv[0], uv[1]); wu.y = cvt_pk_bf16(uv[2], uv[3]); wu.z = cvt_pk_bf16(uv[4], uv[5]); wu.w = cvt_pk_bf16(uv[6], uv[7]);
;                 *(u32x4*)(Ao + off) = wa; *(u32x4*)(Uo + off) = wu; asm volatile("" ::: "memory"); }
.LBB0_384:
	v_sub_f32_e32 v78, 2.0, v54
	v_mul_f32_e32 v78, v54, v78
	v_add_f32_e32 v46, v46, v42
	v_mul_f32_e32 v46, 0xbfb8aa3b, v46
	v_sqrt_f32_e32 v79, v78
	v_exp_f32_e32 v46, v46
	v_add_f32_e32 v47, v47, v43
	v_mul_f32_e32 v47, 0xbfb8aa3b, v47
	v_add_f32_e32 v46, 1.0, v46
	v_rcp_f32_e32 v46, v46
	v_exp_f32_e32 v47, v47
	s_waitcnt vmcnt(0)
	v_lshlrev_b32_e32 v80, 16, v75
	v_mul_f32_e32 v46, v46, v80
	v_add_f32_e32 v45, v45, v41
	v_mov_b32_e32 v78, v79
	v_mul_f32_e32 v78, v46, v78
	v_add_f32_e32 v46, 1.0, v47
	v_sub_f32_e32 v47, 2.0, v53
	v_mul_f32_e32 v47, v53, v47
	v_mul_f32_e32 v45, 0xbfb8aa3b, v45
	v_exp_f32_e32 v45, v45
	v_sqrt_f32_e32 v79, v47
	v_and_b32_e32 v80, 0xffff0000, v74
	v_add_f32_e32 v45, 1.0, v45
	v_rcp_f32_e32 v45, v45
	s_nop 0
	v_mul_f32_e32 v45, v45, v80
	v_add_f32_e32 v44, v44, v40
	v_mul_f32_e32 v44, 0xbfb8aa3b, v44
	v_exp_f32_e32 v44, v44
	v_lshlrev_b32_e32 v74, 16, v74
	v_mov_b32_e32 v47, v79
	v_mul_f32_e32 v47, v45, v47
	v_sub_f32_e32 v45, 2.0, v52
	v_mul_f32_e32 v45, v52, v45
	v_add_f32_e32 v44, 1.0, v44
	v_rcp_f32_e32 v44, v44
	v_sqrt_f32_e32 v79, v45
	v_add_f32_e32 v39, v39, v35
	v_mul_f32_e32 v44, v44, v74
	v_mul_f32_e32 v39, 0xbfb8aa3b, v39
	v_exp_f32_e32 v39, v39
	s_nop 0
	v_add_f32_e32 v39, 1.0, v39
	v_rcp_f32_e32 v39, v39
	v_add_f32_e32 v38, v38, v34
	v_mul_f32_e32 v38, 0xbfb8aa3b, v38
	v_mov_b32_e32 v45, v79
	v_mul_f32_e32 v74, v44, v45
	v_sub_f32_e32 v44, 2.0, v63
	v_mul_f32_e32 v44, v63, v44
	v_and_b32_e32 v79, 0xffff0000, v73
	v_mul_f32_e32 v39, v39, v79
	v_sqrt_f32_e32 v45, v44
	v_exp_f32_e32 v38, v38
	v_lshlrev_b32_e32 v73, 16, v73
	v_add_f32_e32 v37, v37, v33
	v_add_f32_e32 v38, 1.0, v38
	v_rcp_f32_e32 v38, v38
	v_mul_f32_e32 v37, 0xbfb8aa3b, v37
	v_mul_f32_e32 v38, v38, v73
	v_exp_f32_e32 v37, v37
	v_mov_b32_e32 v44, v45
	v_mul_f32_e32 v45, v39, v44
	v_sub_f32_e32 v39, 2.0, v62
	v_mul_f32_e32 v39, v62, v39
	v_add_f32_e32 v37, 1.0, v37
	v_rcp_f32_e32 v37, v37
	v_sqrt_f32_e32 v44, v39
	v_add_f32_e32 v36, v36, v32
	v_mul_f32_e32 v36, 0xbfb8aa3b, v36
	v_exp_f32_e32 v36, v36
	s_nop 0
	v_add_f32_e32 v36, 1.0, v36
	v_rcp_f32_e32 v36, v36
	v_rcp_f32_e32 v46, v46
	v_add_f32_e32 v28, v28, v64
	v_mul_f32_e32 v28, 0xbfb8aa3b, v28
	v_mov_b32_e32 v39, v44
	v_mul_f32_e32 v73, v38, v39
	v_sub_f32_e32 v38, 2.0, v61
	v_mul_f32_e32 v38, v61, v38
	v_and_b32_e32 v44, 0xffff0000, v72
	v_mul_f32_e32 v37, v37, v44
	v_sqrt_f32_e32 v39, v38
	v_exp_f32_e32 v28, v28
	s_nop 0
	v_add_f32_e32 v28, 1.0, v28
	v_rcp_f32_e32 v28, v28
	s_nop 0
	s_nop 1
	s_nop 0
	v_mov_b32_e32 v38, v39
	v_mul_f32_e32 v44, v37, v38
	v_sub_f32_e32 v37, 2.0, v60
	v_mul_f32_e32 v37, v60, v37
	v_lshlrev_b32_e32 v39, 16, v72
	v_mul_f32_e32 v36, v36, v39
	v_sqrt_f32_e32 v38, v37
	s_nop 0
	s_nop 0
	s_nop 1
	s_nop 1
	s_nop 0
	v_mov_b32_e32 v37, v38
	v_sub_f32_e32 v38, 2.0, v55
	v_mul_f32_e32 v38, v55, v38
	v_mul_f32_e32 v79, v36, v37
	v_and_b32_e32 v36, 0xffff0000, v75
	v_sqrt_f32_e32 v72, v38
	v_mul_f32_e32 v36, v46, v36
	s_nop 0
	s_nop 1
	s_mov_b64 s[0:1], 0x50000
	s_nop 0
	v_mov_b32_e32 v37, v72
	v_mul_f32_e32 v72, v36, v37
	v_cvt_pk_bf16_f32 v36, v60, v61
	v_cvt_pk_bf16_f32 v37, v62, v63
	v_cvt_pk_bf16_f32 v38, v52, v53
	v_lshlrev_b64 v[52:53], 1, v[76:77]
	v_cvt_pk_bf16_f32 v39, v54, v55
	v_lshl_add_u64 v[54:55], s[12:13], 0, v[52:53]
	v_cvt_pk_bf16_f32 v44, v79, v44
	v_cvt_pk_bf16_f32 v45, v73, v45
	v_cvt_pk_bf16_f32 v46, v74, v47
	v_cvt_pk_bf16_f32 v47, v78, v72
	global_store_dwordx4 v[54:55], v[36:39], off
	s_nop 1
	v_lshl_add_u64 v[36:37], s[16:17], 0, v[52:53]
	global_store_dwordx4 v[36:37], v[44:47], off
	v_lshlrev_b64 v[36:37], 11, v[182:183]
	v_lshl_add_u64 v[36:37], v[36:37], 0, v[180:181]
	v_lshl_add_u64 v[44:45], v[36:37], 0, s[0:1]
	v_readlane_b32 s0, v252, 6
	v_readlane_b32 s1, v252, 7
	v_mul_f32_e32 v46, v68, v28
	v_fmamk_f32 v28, v46, 0xbc088889, v163
	v_lshl_add_u64 v[36:37], v[44:45], 1, s[0:1]
	global_load_dwordx4 v[36:39], v[36:37], off
	v_fma_f32 v28, -v46, v28, s5
	v_fma_f32 v28, -v46, v28, 0.5
	v_fma_f32 v28, -v46, v28, 1.0
	v_mul_f32_e32 v28, v46, v28
	v_cmp_le_f32_e32 vcc, s8, v46
	s_cbranch_vccnz .LBB0_452

; __device__ __forceinline__ float bf2f(unsigned b) { return __uint_as_float(b << 16); }
; __device__ __forceinline__ unsigned cvt_pk_bf16(float lo, float hi) { unsigned r; asm volatile("v_cvt_pk_bf16_f32 %0, %1, %2" : "=v"(r) : "v"(lo), "v"(hi)); return r; }
; __device__ __forceinline__ float fsigmoid(float x) { return __builtin_amdgcn_rcpf(1.0f + __expf(-x)); }
;     __device__ __forceinline__ void operator()(const Acc& acc, const Unit& u, int wr, int wc, int fr, int fq) const {
;     ...
;             for (int m = 0; m < 4; ++m) { const int row = row0 + ai * HALF + m * 16; const size_t off = (size_t)row * DM + ch0;
;                 const u32x4 xw = *(const u32x4*)(xc + off);
;                 const float xv[8] = {bf2f(xw.x & 0xffffu), bf2f(xw.x >> 16), bf2f(xw.y & 0xffffu), bf2f(xw.y >> 16), bf2f(xw.z & 0xffffu), bf2f(xw.z >> 16), bf2f(xw.w & 0xffffu), bf2f(xw.w >> 16)};
;                 float om[8], uv[8];
; #pragma unroll
;                 for (int n = 0; n < 2; ++n)
; #pragma unroll
;                     for (int j = 0; j < 4; ++j) { const float r = fsigmoid(acc[ai][0][m][n][j] + ba[n][j]), ig = fsigmoid(acc[ai][1][m][n][j] + bi[n][j]);
;                         const float y = r * cc[n][j];
;                         float o1 = y * (1.0f - y * (0.5f - y * (0.16666667f - y * (0.041666668f - y * 0.008333334f))));
;                         if (__builtin_expect(__any(y >= 0.125f), 0)) { const float ome = 1.0f - __expf(-y); o1 = y < 0.125f ? o1 : ome; }
;                         om[n * 4 + j] = o1; uv[n * 4 + j] = sqrtf(o1 * (2.0f - o1)) * (ig * xv[n * 4 + j]); }
;                 u32x4 wa, wu; wa.x = cvt_pk_bf16(om[0], om[1]); wa.y = cvt_pk_bf16(om[2], om[3]); wa.z = cvt_pk_bf16(om[4], om[5]); wa.w = cvt_pk_bf16(om[6], om[7]);
;                 wu.x = cvt_pk_bf16(uv[0], uv[1]); wu.y = cvt_pk_bf16(uv[2], uv[3]); wu.z = cvt_pk_bf16(uv[4], uv[5]); wu.w = cvt_pk_bf16(uv[6], uv[7]);
;                 *(u32x4*)(Ao + off) = wa; *(u32x4*)(Uo + off) = wu; asm volatile("" ::: "memory"); }
.LBB0_392:
	v_sub_f32_e32 v46, 2.0, v26
	v_mul_f32_e32 v46, v26, v46
	v_add_f32_e32 v22, v22, v42
	v_mul_f32_e32 v22, 0xbfb8aa3b, v22
	v_sqrt_f32_e32 v47, v46
	v_exp_f32_e32 v22, v22
	v_add_f32_e32 v23, v23, v43
	v_mul_f32_e32 v23, 0xbfb8aa3b, v23
	v_add_f32_e32 v22, 1.0, v22
	v_rcp_f32_e32 v22, v22
	v_exp_f32_e32 v23, v23
	s_waitcnt vmcnt(0)
	v_lshlrev_b32_e32 v52, 16, v39
	v_mul_f32_e32 v22, v22, v52
	v_add_f32_e32 v21, v21, v41
	v_mov_b32_e32 v46, v47
	v_mul_f32_e32 v46, v22, v46
	v_add_f32_e32 v22, 1.0, v23
	v_sub_f32_e32 v23, 2.0, v25
	v_mul_f32_e32 v23, v25, v23
	v_mul_f32_e32 v21, 0xbfb8aa3b, v21
	v_exp_f32_e32 v21, v21
	v_sqrt_f32_e32 v47, v23
	v_and_b32_e32 v52, 0xffff0000, v38
	v_add_f32_e32 v21, 1.0, v21
	v_rcp_f32_e32 v21, v21
	s_nop 0
	v_mul_f32_e32 v21, v21, v52
	v_add_f32_e32 v20, v20, v40
	v_mul_f32_e32 v20, 0xbfb8aa3b, v20
	v_exp_f32_e32 v20, v20
	v_lshlrev_b32_e32 v38, 16, v38
	v_mov_b32_e32 v23, v47
	v_mul_f32_e32 v23, v21, v23
	v_sub_f32_e32 v21, 2.0, v24
	v_mul_f32_e32 v21, v24, v21
	v_add_f32_e32 v20, 1.0, v20
	v_rcp_f32_e32 v20, v20
	v_sqrt_f32_e32 v47, v21
	v_add_f32_e32 v19, v19, v35
	v_mul_f32_e32 v20, v20, v38
	v_mul_f32_e32 v19, 0xbfb8aa3b, v19
	v_exp_f32_e32 v19, v19
	s_nop 0
	v_add_f32_e32 v19, 1.0, v19
	v_rcp_f32_e32 v19, v19
	v_add_f32_e32 v18, v18, v34
	v_mul_f32_e32 v18, 0xbfb8aa3b, v18
	v_mov_b32_e32 v21, v47
	v_mul_f32_e32 v38, v20, v21
	v_sub_f32_e32 v20, 2.0, v31
	v_mul_f32_e32 v20, v31, v20
	v_and_b32_e32 v47, 0xffff0000, v37
	v_mul_f32_e32 v19, v19, v47
	v_sqrt_f32_e32 v21, v20
	v_exp_f32_e32 v18, v18
	v_lshlrev_b32_e32 v37, 16, v37
	v_add_f32_e32 v17, v17, v33
	v_add_f32_e32 v18, 1.0, v18
	v_rcp_f32_e32 v18, v18
	v_mul_f32_e32 v17, 0xbfb8aa3b, v17
	v_mul_f32_e32 v18, v18, v37
	v_exp_f32_e32 v17, v17
	v_mov_b32_e32 v20, v21
	v_mul_f32_e32 v21, v19, v20
	v_sub_f32_e32 v19, 2.0, v30
	v_mul_f32_e32 v19, v30, v19
	v_add_f32_e32 v17, 1.0, v17
	v_rcp_f32_e32 v17, v17
	v_sqrt_f32_e32 v20, v19
	v_add_f32_e32 v16, v16, v32
	v_mul_f32_e32 v16, 0xbfb8aa3b, v16
	v_exp_f32_e32 v16, v16
	s_nop 0
	v_add_f32_e32 v16, 1.0, v16
	v_rcp_f32_e32 v16, v16
	v_rcp_f32_e32 v22, v22
	v_add_f32_e32 v12, v12, v64
	v_mul_f32_e32 v12, 0xbfb8aa3b, v12
	v_mov_b32_e32 v19, v20
	v_mul_f32_e32 v37, v18, v19
	v_sub_f32_e32 v18, 2.0, v29
	v_mul_f32_e32 v18, v29, v18
	v_and_b32_e32 v20, 0xffff0000, v36
	v_mul_f32_e32 v17, v17, v20
	v_sqrt_f32_e32 v19, v18
	v_exp_f32_e32 v12, v12
	s_nop 0
	v_add_f32_e32 v12, 1.0, v12
	v_rcp_f32_e32 v12, v12
	s_nop 0
	s_nop 1
	s_nop 0
	v_mov_b32_e32 v18, v19
	v_mul_f32_e32 v20, v17, v18
	v_sub_f32_e32 v17, 2.0, v28
	v_mul_f32_e32 v17, v28, v17
	v_lshlrev_b32_e32 v19, 16, v36
	v_mul_f32_e32 v16, v16, v19
	v_sqrt_f32_e32 v18, v17
	s_nop 0
	s_nop 0
	s_nop 1
	s_nop 1
	s_nop 0
	v_mov_b32_e32 v17, v18
	v_sub_f32_e32 v18, 2.0, v27
	v_mul_f32_e32 v18, v27, v18
	v_mul_f32_e32 v47, v16, v17
	v_and_b32_e32 v16, 0xffff0000, v39
	v_sqrt_f32_e32 v36, v18
	v_mul_f32_e32 v16, v22, v16
	s_nop 0
	s_nop 1
	s_mov_b64 s[0:1], 0x58000
	s_nop 0
	v_mov_b32_e32 v17, v36
	v_mul_f32_e32 v36, v16, v17
	v_cvt_pk_bf16_f32 v16, v28, v29
	v_cvt_pk_bf16_f32 v17, v30, v31
	v_cvt_pk_bf16_f32 v18, v24, v25
	v_lshlrev_b64 v[24:25], 1, v[44:45]
	v_cvt_pk_bf16_f32 v19, v26, v27
	v_lshl_add_u64 v[26:27], s[12:13], 0, v[24:25]
	v_cvt_pk_bf16_f32 v20, v47, v20
	v_cvt_pk_bf16_f32 v21, v37, v21
	v_cvt_pk_bf16_f32 v22, v38, v23
	v_cvt_pk_bf16_f32 v23, v46, v36
	global_store_dwordx4 v[26:27], v[16:19], off
	s_nop 1
	v_lshl_add_u64 v[16:17], s[16:17], 0, v[24:25]
	global_store_dwordx4 v[16:17], v[20:23], off
	v_lshlrev_b64 v[16:17], 11, v[182:183]
	v_lshl_add_u64 v[16:17], v[16:17], 0, v[180:181]
	v_lshl_add_u64 v[20:21], v[16:17], 0, s[0:1]
	v_readlane_b32 s0, v252, 6
	v_readlane_b32 s1, v252, 7
	v_mul_f32_e32 v22, v68, v12
	v_fmamk_f32 v12, v22, 0xbc088889, v163
	v_lshl_add_u64 v[16:17], v[20:21], 1, s[0:1]
	global_load_dwordx4 v[16:19], v[16:17], off
	v_fma_f32 v12, -v22, v12, s5
	v_fma_f32 v12, -v22, v12, 0.5
	v_fma_f32 v12, -v22, v12, 1.0
	v_mul_f32_e32 v12, v22, v12
	v_cmp_le_f32_e32 vcc, s8, v22
	s_cbranch_vccnz .LBB0_460
